# P10 conv+SiLU hand-written: next task's 28 loads issued before computing the current one (two register sets), same arithmetic
# speedup vs baseline: 1.0002x; 1.0002x over previous
.LBB0_1005:
	s_cmp_lt_i32 s34, 11
	s_cselect_b64 s[10:11], -1, 0
	s_and_b64 s[6:7], s[10:11], s[6:7]
	s_andn2_b64 vcc, exec, s[6:7]
	s_cbranch_vccnz .LBB0_1012
	v_lshl_or_b32 v1, s2, 9, v0
	s_waitcnt lgkmcnt(0)
	s_mov_b32 s3, 0x160000
	v_cmp_gt_i32_e32 vcc, s3, v1
	s_and_saveexec_b64 s[12:13], vcc
	s_cbranch_execz .LBB0_1011
	s_load_dword s3, s[0:1], 0xd8
	s_add_u32 s14, s70, 0x7900000
	s_addc_u32 s15, s71, 0
	s_add_u32 s16, s14, 0x2c00
	s_addc_u32 s17, s15, 0
	s_add_u32 s18, s70, 0x1600000
	s_addc_u32 s19, s71, 0
	s_add_u32 s20, s54, 0xb000
	s_addc_u32 s21, s55, 0
	s_mov_b64 s[22:23], s[54:55]
	s_add_u32 s24, s54, 0x16000
	s_addc_u32 s25, s55, 0
	s_add_u32 s26, s54, 0x10800
	s_addc_u32 s27, s55, 0
	s_add_u32 s28, s54, 0x5800
	s_addc_u32 s29, s55, 0
	s_add_u32 s30, s54, 0x1b800
	s_addc_u32 s31, s55, 0
	s_add_u32 s36, s56, 0x5800
	s_addc_u32 s37, s57, 0
	s_mov_b32 s38, 0x2e8ba2e9
	s_mov_b32 s39, 0x160000
	s_waitcnt lgkmcnt(0)
	s_lshl_b32 s3, s3, 9
	s_mov_b64 s[6:7], exec
	v_mov_b32_e32 v216, 0
	v_mov_b32_e32 v154, v1
	v_mul_hi_u32 v2, v154, s38
	v_lshrrev_b32_e32 v2, 8, v2
	v_mul_u32_u24_e32 v3, 0x580, v2
	v_sub_u32_e32 v3, v154, v3
	v_lshlrev_b32_e32 v4, 3, v3
	v_and_b32_e32 v5, 0x1ff, v2
	v_cmp_eq_u32_e32 vcc, 0, v5
	s_nop 1
	v_cndmask_b32_e64 v153, 0, 1, vcc
	v_lshlrev_b32_e32 v5, 3, v2
	v_mul_u32_u24_e32 v6, 0x2c00, v5
	v_add_u32_e32 v152, v6, v4
	v_mul_u32_u24_e32 v6, 0x5800, v5
	v_add_u32_e32 v6, v6, v4
	v_add_u32_e32 v7, 0xffff5000, v6
	v_cndmask_b32_e32 v7, v7, v6, vcc
	global_load_dwordx2 v[8:9], v7, s[14:15]
	global_load_dwordx2 v[28:29], v7, s[16:17]
	v_add_u32_e32 v7, 0xffffa800, v6
	v_cndmask_b32_e32 v7, v7, v6, vcc
	global_load_dwordx2 v[10:11], v7, s[14:15]
	global_load_dwordx2 v[30:31], v7, s[16:17]
	global_load_dwordx2 v[12:13], v6, s[14:15]
	global_load_dwordx2 v[32:33], v6, s[16:17]
	v_add_u32_e32 v6, 0x5800, v6
	global_load_dwordx2 v[14:15], v6, s[14:15]
	global_load_dwordx2 v[34:35], v6, s[16:17]
	v_add_u32_e32 v6, 0x5800, v6
	global_load_dwordx2 v[16:17], v6, s[14:15]
	global_load_dwordx2 v[36:37], v6, s[16:17]
	v_add_u32_e32 v6, 0x5800, v6
	global_load_dwordx2 v[18:19], v6, s[14:15]
	global_load_dwordx2 v[38:39], v6, s[16:17]
	v_add_u32_e32 v6, 0x5800, v6
	global_load_dwordx2 v[20:21], v6, s[14:15]
	global_load_dwordx2 v[40:41], v6, s[16:17]
	v_add_u32_e32 v6, 0x5800, v6
	global_load_dwordx2 v[22:23], v6, s[14:15]
	global_load_dwordx2 v[42:43], v6, s[16:17]
	v_add_u32_e32 v6, 0x5800, v6
	global_load_dwordx2 v[24:25], v6, s[14:15]
	global_load_dwordx2 v[44:45], v6, s[16:17]
	v_add_u32_e32 v6, 0x5800, v6
	global_load_dwordx2 v[26:27], v6, s[14:15]
	global_load_dwordx2 v[46:47], v6, s[16:17]
	v_lshlrev_b32_e32 v4, 4, v3
	global_load_dwordx4 v[48:51], v4, s[20:21]
	global_load_dwordx4 v[52:55], v4, s[22:23]
	global_load_dwordx4 v[56:59], v4, s[24:25]
	global_load_dwordx4 v[60:63], v4, s[56:57]
	global_load_dwordx4 v[64:67], v4, s[26:27]
	global_load_dwordx4 v[68:71], v4, s[28:29]
	global_load_dwordx4 v[72:75], v4, s[30:31]
	global_load_dwordx4 v[76:79], v4, s[36:37]
	global_store_dwordx2 v152, v[216:217], s[18:19]
	v_add_u32_e32 v152, 0x2c00, v152
	global_store_dwordx2 v152, v[216:217], s[18:19]
	v_add_u32_e32 v152, 0x2c00, v152
	global_store_dwordx2 v152, v[216:217], s[18:19]
	v_add_u32_e32 v152, 0x2c00, v152
	global_store_dwordx2 v152, v[216:217], s[18:19]
	v_add_u32_e32 v152, 0x2c00, v152
	global_store_dwordx2 v152, v[216:217], s[18:19]
	v_add_u32_e32 v152, 0x2c00, v152
	global_store_dwordx2 v152, v[216:217], s[18:19]
	v_add_u32_e32 v152, 0x2c00, v152
	global_store_dwordx2 v152, v[216:217], s[18:19]
	v_add_u32_e32 v152, 0x2c00, v152
	global_store_dwordx2 v152, v[216:217], s[18:19]
	v_add_u32_e32 v152, 0xfffecc00, v152
	v_mov_b32_e32 v217, 0
.Lcv_loop:
	v_add_u32_e32 v158, s3, v154
	v_cmp_gt_u32_e32 vcc, s39, v158
	s_and_b64 s[8:9], vcc, exec
	s_nop 0
	v_cndmask_b32_e32 v218, v154, v158, vcc
	v_mul_hi_u32 v2, v218, s38
	v_lshrrev_b32_e32 v2, 8, v2
	v_mul_u32_u24_e32 v3, 0x580, v2
	v_sub_u32_e32 v3, v218, v3
	v_lshlrev_b32_e32 v4, 3, v3
	v_and_b32_e32 v5, 0x1ff, v2
	v_cmp_eq_u32_e32 vcc, 0, v5
	s_nop 1
	v_cndmask_b32_e64 v157, 0, 1, vcc
	v_lshlrev_b32_e32 v5, 3, v2
	v_mul_u32_u24_e32 v6, 0x2c00, v5
	v_add_u32_e32 v156, v6, v4
	v_mul_u32_u24_e32 v6, 0x5800, v5
	v_add_u32_e32 v6, v6, v4
	v_add_u32_e32 v7, 0xffff5000, v6
	v_cndmask_b32_e32 v7, v7, v6, vcc
	global_load_dwordx2 v[80:81], v7, s[14:15]
	global_load_dwordx2 v[100:101], v7, s[16:17]
	v_add_u32_e32 v7, 0xffffa800, v6
	v_cndmask_b32_e32 v7, v7, v6, vcc
	global_load_dwordx2 v[82:83], v7, s[14:15]
	global_load_dwordx2 v[102:103], v7, s[16:17]
	global_load_dwordx2 v[84:85], v6, s[14:15]
	global_load_dwordx2 v[104:105], v6, s[16:17]
	v_add_u32_e32 v6, 0x5800, v6
	global_load_dwordx2 v[86:87], v6, s[14:15]
	global_load_dwordx2 v[106:107], v6, s[16:17]
	v_add_u32_e32 v6, 0x5800, v6
	global_load_dwordx2 v[88:89], v6, s[14:15]
	global_load_dwordx2 v[108:109], v6, s[16:17]
	v_add_u32_e32 v6, 0x5800, v6
	global_load_dwordx2 v[90:91], v6, s[14:15]
	global_load_dwordx2 v[110:111], v6, s[16:17]
	v_add_u32_e32 v6, 0x5800, v6
	global_load_dwordx2 v[92:93], v6, s[14:15]
	global_load_dwordx2 v[112:113], v6, s[16:17]
	v_add_u32_e32 v6, 0x5800, v6
	global_load_dwordx2 v[94:95], v6, s[14:15]
	global_load_dwordx2 v[114:115], v6, s[16:17]
	v_add_u32_e32 v6, 0x5800, v6
	global_load_dwordx2 v[96:97], v6, s[14:15]
	global_load_dwordx2 v[116:117], v6, s[16:17]
	v_add_u32_e32 v6, 0x5800, v6
	global_load_dwordx2 v[98:99], v6, s[14:15]
	global_load_dwordx2 v[118:119], v6, s[16:17]
	v_lshlrev_b32_e32 v4, 4, v3
	global_load_dwordx4 v[120:123], v4, s[20:21]
	global_load_dwordx4 v[124:127], v4, s[22:23]
	global_load_dwordx4 v[128:131], v4, s[24:25]
	global_load_dwordx4 v[132:135], v4, s[56:57]
	global_load_dwordx4 v[136:139], v4, s[26:27]
	global_load_dwordx4 v[140:143], v4, s[28:29]
	global_load_dwordx4 v[144:147], v4, s[30:31]
	global_load_dwordx4 v[148:151], v4, s[36:37]
	s_mov_b64 s[38:39], s[8:9]
	s_waitcnt vmcnt(36)
	v_cmp_ne_u32_e32 vcc, 0, v153
	s_nop 1
	v_cndmask_b32_e32 v8, v8, v216, vcc
	v_cndmask_b32_e32 v9, v9, v216, vcc
	v_cndmask_b32_e32 v10, v10, v216, vcc
	v_cndmask_b32_e32 v11, v11, v216, vcc
	v_cndmask_b32_e32 v28, v28, v216, vcc
	v_cndmask_b32_e32 v29, v29, v216, vcc
	v_cndmask_b32_e32 v30, v30, v216, vcc
	v_cndmask_b32_e32 v31, v31, v216, vcc
	v_lshlrev_b32_e32 v160, 16, v8
	v_and_b32_e32 v161, 0xffff0000, v8
	v_lshlrev_b32_e32 v162, 16, v9
	v_and_b32_e32 v163, 0xffff0000, v9
	v_lshlrev_b32_e32 v172, 16, v28
	v_and_b32_e32 v173, 0xffff0000, v28
	v_lshlrev_b32_e32 v174, 16, v29
	v_and_b32_e32 v175, 0xffff0000, v29
	v_lshlrev_b32_e32 v164, 16, v10
	v_and_b32_e32 v165, 0xffff0000, v10
	v_lshlrev_b32_e32 v166, 16, v11
	v_and_b32_e32 v167, 0xffff0000, v11
	v_lshlrev_b32_e32 v176, 16, v30
	v_and_b32_e32 v177, 0xffff0000, v30
	v_lshlrev_b32_e32 v178, 16, v31
	v_and_b32_e32 v179, 0xffff0000, v31
	v_lshlrev_b32_e32 v168, 16, v12
	v_and_b32_e32 v169, 0xffff0000, v12
	v_lshlrev_b32_e32 v170, 16, v13
	v_and_b32_e32 v171, 0xffff0000, v13
	v_lshlrev_b32_e32 v180, 16, v32
	v_and_b32_e32 v181, 0xffff0000, v32
	v_lshlrev_b32_e32 v182, 16, v33
	v_and_b32_e32 v183, 0xffff0000, v33
	v_pk_mul_f32 v[184:185], v[48:49], v[164:165]
	v_pk_mul_f32 v[188:189], v[64:65], v[176:177]
	v_pk_fma_f32 v[184:185], v[52:53], v[160:161], v[184:185]
	v_pk_fma_f32 v[188:189], v[68:69], v[172:173], v[188:189]
	v_pk_fma_f32 v[184:185], v[56:57], v[168:169], v[184:185]
	v_pk_fma_f32 v[188:189], v[72:73], v[180:181], v[188:189]
	v_pk_add_f32 v[184:185], v[184:185], v[60:61]
	v_pk_add_f32 v[188:189], v[188:189], v[76:77]
	v_pk_mul_f32 v[186:187], v[50:51], v[166:167]
	v_pk_mul_f32 v[190:191], v[66:67], v[178:179]
	v_pk_fma_f32 v[186:187], v[54:55], v[162:163], v[186:187]
	v_pk_fma_f32 v[190:191], v[70:71], v[174:175], v[190:191]
	v_pk_fma_f32 v[186:187], v[58:59], v[170:171], v[186:187]
	v_pk_fma_f32 v[190:191], v[74:75], v[182:183], v[190:191]
	v_pk_add_f32 v[186:187], v[186:187], v[62:63]
	v_pk_add_f32 v[190:191], v[190:191], v[78:79]
	v_mul_f32_e32 v192, 0xbfb8aa3b, v188
	v_mul_f32_e32 v193, 0xbfb8aa3b, v189
	v_mul_f32_e32 v194, 0xbfb8aa3b, v190
	v_mul_f32_e32 v195, 0xbfb8aa3b, v191
	v_exp_f32_e32 v192, v192
	v_exp_f32_e32 v193, v193
	v_exp_f32_e32 v194, v194
	v_exp_f32_e32 v195, v195
	s_nop 0
	v_pk_add_f32 v[192:193], v[192:193], 1.0 op_sel_hi:[1,0]
	v_pk_add_f32 v[194:195], v[194:195], 1.0 op_sel_hi:[1,0]
	v_div_scale_f32 v200, s[8:9], v192, v192, 1.0
	v_div_scale_f32 v201, vcc, 1.0, v192, 1.0
	v_rcp_f32_e32 v202, v200
	s_nop 0
	v_fma_f32 v204, -v200, v202, 1.0
	v_fmac_f32_e32 v202, v204, v202
	v_mul_f32_e32 v203, v201, v202
	v_fma_f32 v204, -v200, v203, v201
	v_fmac_f32_e32 v203, v204, v202
	v_fma_f32 v204, -v200, v203, v201
	v_div_fmas_f32 v204, v204, v202, v203
	v_div_fixup_f32 v196, v204, v192, 1.0
	v_div_scale_f32 v200, s[8:9], v193, v193, 1.0
	v_div_scale_f32 v201, vcc, 1.0, v193, 1.0
	v_rcp_f32_e32 v202, v200
	s_nop 0
	v_fma_f32 v204, -v200, v202, 1.0
	v_fmac_f32_e32 v202, v204, v202
	v_mul_f32_e32 v203, v201, v202
	v_fma_f32 v204, -v200, v203, v201
	v_fmac_f32_e32 v203, v204, v202
	v_fma_f32 v204, -v200, v203, v201
	v_div_fmas_f32 v204, v204, v202, v203
	v_div_fixup_f32 v197, v204, v193, 1.0
	v_div_scale_f32 v200, s[8:9], v194, v194, 1.0
	v_div_scale_f32 v201, vcc, 1.0, v194, 1.0
	v_rcp_f32_e32 v202, v200
	s_nop 0
	v_fma_f32 v204, -v200, v202, 1.0
	v_fmac_f32_e32 v202, v204, v202
	v_mul_f32_e32 v203, v201, v202
	v_fma_f32 v204, -v200, v203, v201
	v_fmac_f32_e32 v203, v204, v202
	v_fma_f32 v204, -v200, v203, v201
	v_div_fmas_f32 v204, v204, v202, v203
	v_div_fixup_f32 v198, v204, v194, 1.0
	v_div_scale_f32 v200, s[8:9], v195, v195, 1.0
	v_div_scale_f32 v201, vcc, 1.0, v195, 1.0
	v_rcp_f32_e32 v202, v200
	s_nop 0
	v_fma_f32 v204, -v200, v202, 1.0
	v_fmac_f32_e32 v202, v204, v202
	v_mul_f32_e32 v203, v201, v202
	v_fma_f32 v204, -v200, v203, v201
	v_fmac_f32_e32 v203, v204, v202
	v_fma_f32 v204, -v200, v203, v201
	v_div_fmas_f32 v204, v204, v202, v203
	v_div_fixup_f32 v199, v204, v195, 1.0
	v_pk_mul_f32 v[196:197], v[188:189], v[196:197]
	v_pk_mul_f32 v[198:199], v[190:191], v[198:199]
	v_pk_mul_f32 v[196:197], v[184:185], v[196:197]
	v_pk_mul_f32 v[198:199], v[186:187], v[198:199]
	v_cvt_pk_bf16_f32 v206, v196, v197
	v_cvt_pk_bf16_f32 v207, v198, v199
	global_store_dwordx2 v152, v[206:207], s[18:19]
	v_lshlrev_b32_e32 v160, 16, v14
	v_and_b32_e32 v161, 0xffff0000, v14
	v_lshlrev_b32_e32 v162, 16, v15
	v_and_b32_e32 v163, 0xffff0000, v15
	v_lshlrev_b32_e32 v172, 16, v34
	v_and_b32_e32 v173, 0xffff0000, v34
	v_lshlrev_b32_e32 v174, 16, v35
	v_and_b32_e32 v175, 0xffff0000, v35
	v_pk_mul_f32 v[184:185], v[48:49], v[168:169]
	v_pk_mul_f32 v[188:189], v[64:65], v[180:181]
	v_pk_fma_f32 v[184:185], v[52:53], v[164:165], v[184:185]
	v_pk_fma_f32 v[188:189], v[68:69], v[176:177], v[188:189]
	v_pk_fma_f32 v[184:185], v[56:57], v[160:161], v[184:185]
	v_pk_fma_f32 v[188:189], v[72:73], v[172:173], v[188:189]
	v_pk_add_f32 v[184:185], v[184:185], v[60:61]
	v_pk_add_f32 v[188:189], v[188:189], v[76:77]
	v_pk_mul_f32 v[186:187], v[50:51], v[170:171]
	v_pk_mul_f32 v[190:191], v[66:67], v[182:183]
	v_pk_fma_f32 v[186:187], v[54:55], v[166:167], v[186:187]
	v_pk_fma_f32 v[190:191], v[70:71], v[178:179], v[190:191]
	v_pk_fma_f32 v[186:187], v[58:59], v[162:163], v[186:187]
	v_pk_fma_f32 v[190:191], v[74:75], v[174:175], v[190:191]
	v_pk_add_f32 v[186:187], v[186:187], v[62:63]
	v_pk_add_f32 v[190:191], v[190:191], v[78:79]
	v_mul_f32_e32 v192, 0xbfb8aa3b, v188
	v_mul_f32_e32 v193, 0xbfb8aa3b, v189
	v_mul_f32_e32 v194, 0xbfb8aa3b, v190
	v_mul_f32_e32 v195, 0xbfb8aa3b, v191
	v_exp_f32_e32 v192, v192
	v_exp_f32_e32 v193, v193
	v_exp_f32_e32 v194, v194
	v_exp_f32_e32 v195, v195
	s_nop 0
	v_pk_add_f32 v[192:193], v[192:193], 1.0 op_sel_hi:[1,0]
	v_pk_add_f32 v[194:195], v[194:195], 1.0 op_sel_hi:[1,0]
	v_div_scale_f32 v200, s[8:9], v192, v192, 1.0
	v_div_scale_f32 v201, vcc, 1.0, v192, 1.0
	v_rcp_f32_e32 v202, v200
	s_nop 0
	v_fma_f32 v204, -v200, v202, 1.0
	v_fmac_f32_e32 v202, v204, v202
	v_mul_f32_e32 v203, v201, v202
	v_fma_f32 v204, -v200, v203, v201
	v_fmac_f32_e32 v203, v204, v202
	v_fma_f32 v204, -v200, v203, v201
	v_div_fmas_f32 v204, v204, v202, v203
	v_div_fixup_f32 v196, v204, v192, 1.0
	v_div_scale_f32 v200, s[8:9], v193, v193, 1.0
	v_div_scale_f32 v201, vcc, 1.0, v193, 1.0
	v_rcp_f32_e32 v202, v200
	s_nop 0
	v_fma_f32 v204, -v200, v202, 1.0
	v_fmac_f32_e32 v202, v204, v202
	v_mul_f32_e32 v203, v201, v202
	v_fma_f32 v204, -v200, v203, v201
	v_fmac_f32_e32 v203, v204, v202
	v_fma_f32 v204, -v200, v203, v201
	v_div_fmas_f32 v204, v204, v202, v203
	v_div_fixup_f32 v197, v204, v193, 1.0
	v_div_scale_f32 v200, s[8:9], v194, v194, 1.0
	v_div_scale_f32 v201, vcc, 1.0, v194, 1.0
	v_rcp_f32_e32 v202, v200
	s_nop 0
	v_fma_f32 v204, -v200, v202, 1.0
	v_fmac_f32_e32 v202, v204, v202
	v_mul_f32_e32 v203, v201, v202
	v_fma_f32 v204, -v200, v203, v201
	v_fmac_f32_e32 v203, v204, v202
	v_fma_f32 v204, -v200, v203, v201
	v_div_fmas_f32 v204, v204, v202, v203
	v_div_fixup_f32 v198, v204, v194, 1.0
	v_div_scale_f32 v200, s[8:9], v195, v195, 1.0
	v_div_scale_f32 v201, vcc, 1.0, v195, 1.0
	v_rcp_f32_e32 v202, v200
	s_nop 0
	v_fma_f32 v204, -v200, v202, 1.0
	v_fmac_f32_e32 v202, v204, v202
	v_mul_f32_e32 v203, v201, v202
	v_fma_f32 v204, -v200, v203, v201
	v_fmac_f32_e32 v203, v204, v202
	v_fma_f32 v204, -v200, v203, v201
	v_div_fmas_f32 v204, v204, v202, v203
	v_div_fixup_f32 v199, v204, v195, 1.0
	v_pk_mul_f32 v[196:197], v[188:189], v[196:197]
	v_pk_mul_f32 v[198:199], v[190:191], v[198:199]
	v_pk_mul_f32 v[196:197], v[184:185], v[196:197]
	v_pk_mul_f32 v[198:199], v[186:187], v[198:199]
	v_cvt_pk_bf16_f32 v208, v196, v197
	v_cvt_pk_bf16_f32 v209, v198, v199
	v_add_u32_e32 v152, 0x2c00, v152
	global_store_dwordx2 v152, v[208:209], s[18:19]
	v_lshlrev_b32_e32 v164, 16, v16
	v_and_b32_e32 v165, 0xffff0000, v16
	v_lshlrev_b32_e32 v166, 16, v17
	v_and_b32_e32 v167, 0xffff0000, v17
	v_lshlrev_b32_e32 v176, 16, v36
	v_and_b32_e32 v177, 0xffff0000, v36
	v_lshlrev_b32_e32 v178, 16, v37
	v_and_b32_e32 v179, 0xffff0000, v37
	v_pk_mul_f32 v[184:185], v[48:49], v[160:161]
	v_pk_mul_f32 v[188:189], v[64:65], v[172:173]
	v_pk_fma_f32 v[184:185], v[52:53], v[168:169], v[184:185]
	v_pk_fma_f32 v[188:189], v[68:69], v[180:181], v[188:189]
	v_pk_fma_f32 v[184:185], v[56:57], v[164:165], v[184:185]
	v_pk_fma_f32 v[188:189], v[72:73], v[176:177], v[188:189]
	v_pk_add_f32 v[184:185], v[184:185], v[60:61]
	v_pk_add_f32 v[188:189], v[188:189], v[76:77]
	v_pk_mul_f32 v[186:187], v[50:51], v[162:163]
	v_pk_mul_f32 v[190:191], v[66:67], v[174:175]
	v_pk_fma_f32 v[186:187], v[54:55], v[170:171], v[186:187]
	v_pk_fma_f32 v[190:191], v[70:71], v[182:183], v[190:191]
	v_pk_fma_f32 v[186:187], v[58:59], v[166:167], v[186:187]
	v_pk_fma_f32 v[190:191], v[74:75], v[178:179], v[190:191]
	v_pk_add_f32 v[186:187], v[186:187], v[62:63]
	v_pk_add_f32 v[190:191], v[190:191], v[78:79]
	v_mul_f32_e32 v192, 0xbfb8aa3b, v188
	v_mul_f32_e32 v193, 0xbfb8aa3b, v189
	v_mul_f32_e32 v194, 0xbfb8aa3b, v190
	v_mul_f32_e32 v195, 0xbfb8aa3b, v191
	v_exp_f32_e32 v192, v192
	v_exp_f32_e32 v193, v193
	v_exp_f32_e32 v194, v194
	v_exp_f32_e32 v195, v195
	s_nop 0
	v_pk_add_f32 v[192:193], v[192:193], 1.0 op_sel_hi:[1,0]
	v_pk_add_f32 v[194:195], v[194:195], 1.0 op_sel_hi:[1,0]
	v_div_scale_f32 v200, s[8:9], v192, v192, 1.0
	v_div_scale_f32 v201, vcc, 1.0, v192, 1.0
	v_rcp_f32_e32 v202, v200
	s_nop 0
	v_fma_f32 v204, -v200, v202, 1.0
	v_fmac_f32_e32 v202, v204, v202
	v_mul_f32_e32 v203, v201, v202
	v_fma_f32 v204, -v200, v203, v201
	v_fmac_f32_e32 v203, v204, v202
	v_fma_f32 v204, -v200, v203, v201
	v_div_fmas_f32 v204, v204, v202, v203
	v_div_fixup_f32 v196, v204, v192, 1.0
	v_div_scale_f32 v200, s[8:9], v193, v193, 1.0
	v_div_scale_f32 v201, vcc, 1.0, v193, 1.0
	v_rcp_f32_e32 v202, v200
	s_nop 0
	v_fma_f32 v204, -v200, v202, 1.0
	v_fmac_f32_e32 v202, v204, v202
	v_mul_f32_e32 v203, v201, v202
	v_fma_f32 v204, -v200, v203, v201
	v_fmac_f32_e32 v203, v204, v202
	v_fma_f32 v204, -v200, v203, v201
	v_div_fmas_f32 v204, v204, v202, v203
	v_div_fixup_f32 v197, v204, v193, 1.0
	v_div_scale_f32 v200, s[8:9], v194, v194, 1.0
	v_div_scale_f32 v201, vcc, 1.0, v194, 1.0
	v_rcp_f32_e32 v202, v200
	s_nop 0
	v_fma_f32 v204, -v200, v202, 1.0
	v_fmac_f32_e32 v202, v204, v202
	v_mul_f32_e32 v203, v201, v202
	v_fma_f32 v204, -v200, v203, v201
	v_fmac_f32_e32 v203, v204, v202
	v_fma_f32 v204, -v200, v203, v201
	v_div_fmas_f32 v204, v204, v202, v203
	v_div_fixup_f32 v198, v204, v194, 1.0
	v_div_scale_f32 v200, s[8:9], v195, v195, 1.0
	v_div_scale_f32 v201, vcc, 1.0, v195, 1.0
	v_rcp_f32_e32 v202, v200
	s_nop 0
	v_fma_f32 v204, -v200, v202, 1.0
	v_fmac_f32_e32 v202, v204, v202
	v_mul_f32_e32 v203, v201, v202
	v_fma_f32 v204, -v200, v203, v201
	v_fmac_f32_e32 v203, v204, v202
	v_fma_f32 v204, -v200, v203, v201
	v_div_fmas_f32 v204, v204, v202, v203
	v_div_fixup_f32 v199, v204, v195, 1.0
	v_pk_mul_f32 v[196:197], v[188:189], v[196:197]
	v_pk_mul_f32 v[198:199], v[190:191], v[198:199]
	v_pk_mul_f32 v[196:197], v[184:185], v[196:197]
	v_pk_mul_f32 v[198:199], v[186:187], v[198:199]
	v_cvt_pk_bf16_f32 v206, v196, v197
	v_cvt_pk_bf16_f32 v207, v198, v199
	v_add_u32_e32 v152, 0x2c00, v152
	global_store_dwordx2 v152, v[206:207], s[18:19]
	v_lshlrev_b32_e32 v168, 16, v18
	v_and_b32_e32 v169, 0xffff0000, v18
	v_lshlrev_b32_e32 v170, 16, v19
	v_and_b32_e32 v171, 0xffff0000, v19
	v_lshlrev_b32_e32 v180, 16, v38
	v_and_b32_e32 v181, 0xffff0000, v38
	v_lshlrev_b32_e32 v182, 16, v39
	v_and_b32_e32 v183, 0xffff0000, v39
	v_pk_mul_f32 v[184:185], v[48:49], v[164:165]
	v_pk_mul_f32 v[188:189], v[64:65], v[176:177]
	v_pk_fma_f32 v[184:185], v[52:53], v[160:161], v[184:185]
	v_pk_fma_f32 v[188:189], v[68:69], v[172:173], v[188:189]
	v_pk_fma_f32 v[184:185], v[56:57], v[168:169], v[184:185]
	v_pk_fma_f32 v[188:189], v[72:73], v[180:181], v[188:189]
	v_pk_add_f32 v[184:185], v[184:185], v[60:61]
	v_pk_add_f32 v[188:189], v[188:189], v[76:77]
	v_pk_mul_f32 v[186:187], v[50:51], v[166:167]
	v_pk_mul_f32 v[190:191], v[66:67], v[178:179]
	v_pk_fma_f32 v[186:187], v[54:55], v[162:163], v[186:187]
	v_pk_fma_f32 v[190:191], v[70:71], v[174:175], v[190:191]
	v_pk_fma_f32 v[186:187], v[58:59], v[170:171], v[186:187]
	v_pk_fma_f32 v[190:191], v[74:75], v[182:183], v[190:191]
	v_pk_add_f32 v[186:187], v[186:187], v[62:63]
	v_pk_add_f32 v[190:191], v[190:191], v[78:79]
	v_mul_f32_e32 v192, 0xbfb8aa3b, v188
	v_mul_f32_e32 v193, 0xbfb8aa3b, v189
	v_mul_f32_e32 v194, 0xbfb8aa3b, v190
	v_mul_f32_e32 v195, 0xbfb8aa3b, v191
	v_exp_f32_e32 v192, v192
	v_exp_f32_e32 v193, v193
	v_exp_f32_e32 v194, v194
	v_exp_f32_e32 v195, v195
	s_nop 0
	v_pk_add_f32 v[192:193], v[192:193], 1.0 op_sel_hi:[1,0]
	v_pk_add_f32 v[194:195], v[194:195], 1.0 op_sel_hi:[1,0]
	v_div_scale_f32 v200, s[8:9], v192, v192, 1.0
	v_div_scale_f32 v201, vcc, 1.0, v192, 1.0
	v_rcp_f32_e32 v202, v200
	s_nop 0
	v_fma_f32 v204, -v200, v202, 1.0
	v_fmac_f32_e32 v202, v204, v202
	v_mul_f32_e32 v203, v201, v202
	v_fma_f32 v204, -v200, v203, v201
	v_fmac_f32_e32 v203, v204, v202
	v_fma_f32 v204, -v200, v203, v201
	v_div_fmas_f32 v204, v204, v202, v203
	v_div_fixup_f32 v196, v204, v192, 1.0
	v_div_scale_f32 v200, s[8:9], v193, v193, 1.0
	v_div_scale_f32 v201, vcc, 1.0, v193, 1.0
	v_rcp_f32_e32 v202, v200
	s_nop 0
	v_fma_f32 v204, -v200, v202, 1.0
	v_fmac_f32_e32 v202, v204, v202
	v_mul_f32_e32 v203, v201, v202
	v_fma_f32 v204, -v200, v203, v201
	v_fmac_f32_e32 v203, v204, v202
	v_fma_f32 v204, -v200, v203, v201
	v_div_fmas_f32 v204, v204, v202, v203
	v_div_fixup_f32 v197, v204, v193, 1.0
	v_div_scale_f32 v200, s[8:9], v194, v194, 1.0
	v_div_scale_f32 v201, vcc, 1.0, v194, 1.0
	v_rcp_f32_e32 v202, v200
	s_nop 0
	v_fma_f32 v204, -v200, v202, 1.0
	v_fmac_f32_e32 v202, v204, v202
	v_mul_f32_e32 v203, v201, v202
	v_fma_f32 v204, -v200, v203, v201
	v_fmac_f32_e32 v203, v204, v202
	v_fma_f32 v204, -v200, v203, v201
	v_div_fmas_f32 v204, v204, v202, v203
	v_div_fixup_f32 v198, v204, v194, 1.0
	v_div_scale_f32 v200, s[8:9], v195, v195, 1.0
	v_div_scale_f32 v201, vcc, 1.0, v195, 1.0
	v_rcp_f32_e32 v202, v200
	s_nop 0
	v_fma_f32 v204, -v200, v202, 1.0
	v_fmac_f32_e32 v202, v204, v202
	v_mul_f32_e32 v203, v201, v202
	v_fma_f32 v204, -v200, v203, v201
	v_fmac_f32_e32 v203, v204, v202
	v_fma_f32 v204, -v200, v203, v201
	v_div_fmas_f32 v204, v204, v202, v203
	v_div_fixup_f32 v199, v204, v195, 1.0
	v_pk_mul_f32 v[196:197], v[188:189], v[196:197]
	v_pk_mul_f32 v[198:199], v[190:191], v[198:199]
	v_pk_mul_f32 v[196:197], v[184:185], v[196:197]
	v_pk_mul_f32 v[198:199], v[186:187], v[198:199]
	v_cvt_pk_bf16_f32 v208, v196, v197
	v_cvt_pk_bf16_f32 v209, v198, v199
	v_add_u32_e32 v152, 0x2c00, v152
	global_store_dwordx2 v152, v[208:209], s[18:19]
	v_lshlrev_b32_e32 v160, 16, v20
	v_and_b32_e32 v161, 0xffff0000, v20
	v_lshlrev_b32_e32 v162, 16, v21
	v_and_b32_e32 v163, 0xffff0000, v21
	v_lshlrev_b32_e32 v172, 16, v40
	v_and_b32_e32 v173, 0xffff0000, v40
	v_lshlrev_b32_e32 v174, 16, v41
	v_and_b32_e32 v175, 0xffff0000, v41
	v_pk_mul_f32 v[184:185], v[48:49], v[168:169]
	v_pk_mul_f32 v[188:189], v[64:65], v[180:181]
	v_pk_fma_f32 v[184:185], v[52:53], v[164:165], v[184:185]
	v_pk_fma_f32 v[188:189], v[68:69], v[176:177], v[188:189]
	v_pk_fma_f32 v[184:185], v[56:57], v[160:161], v[184:185]
	v_pk_fma_f32 v[188:189], v[72:73], v[172:173], v[188:189]
	v_pk_add_f32 v[184:185], v[184:185], v[60:61]
	v_pk_add_f32 v[188:189], v[188:189], v[76:77]
	v_pk_mul_f32 v[186:187], v[50:51], v[170:171]
	v_pk_mul_f32 v[190:191], v[66:67], v[182:183]
	v_pk_fma_f32 v[186:187], v[54:55], v[166:167], v[186:187]
	v_pk_fma_f32 v[190:191], v[70:71], v[178:179], v[190:191]
	v_pk_fma_f32 v[186:187], v[58:59], v[162:163], v[186:187]
	v_pk_fma_f32 v[190:191], v[74:75], v[174:175], v[190:191]
	v_pk_add_f32 v[186:187], v[186:187], v[62:63]
	v_pk_add_f32 v[190:191], v[190:191], v[78:79]
	v_mul_f32_e32 v192, 0xbfb8aa3b, v188
	v_mul_f32_e32 v193, 0xbfb8aa3b, v189
	v_mul_f32_e32 v194, 0xbfb8aa3b, v190
	v_mul_f32_e32 v195, 0xbfb8aa3b, v191
	v_exp_f32_e32 v192, v192
	v_exp_f32_e32 v193, v193
	v_exp_f32_e32 v194, v194
	v_exp_f32_e32 v195, v195
	s_nop 0
	v_pk_add_f32 v[192:193], v[192:193], 1.0 op_sel_hi:[1,0]
	v_pk_add_f32 v[194:195], v[194:195], 1.0 op_sel_hi:[1,0]
	v_div_scale_f32 v200, s[8:9], v192, v192, 1.0
	v_div_scale_f32 v201, vcc, 1.0, v192, 1.0
	v_rcp_f32_e32 v202, v200
	s_nop 0
	v_fma_f32 v204, -v200, v202, 1.0
	v_fmac_f32_e32 v202, v204, v202
	v_mul_f32_e32 v203, v201, v202
	v_fma_f32 v204, -v200, v203, v201
	v_fmac_f32_e32 v203, v204, v202
	v_fma_f32 v204, -v200, v203, v201
	v_div_fmas_f32 v204, v204, v202, v203
	v_div_fixup_f32 v196, v204, v192, 1.0
	v_div_scale_f32 v200, s[8:9], v193, v193, 1.0
	v_div_scale_f32 v201, vcc, 1.0, v193, 1.0
	v_rcp_f32_e32 v202, v200
	s_nop 0
	v_fma_f32 v204, -v200, v202, 1.0
	v_fmac_f32_e32 v202, v204, v202
	v_mul_f32_e32 v203, v201, v202
	v_fma_f32 v204, -v200, v203, v201
	v_fmac_f32_e32 v203, v204, v202
	v_fma_f32 v204, -v200, v203, v201
	v_div_fmas_f32 v204, v204, v202, v203
	v_div_fixup_f32 v197, v204, v193, 1.0
	v_div_scale_f32 v200, s[8:9], v194, v194, 1.0
	v_div_scale_f32 v201, vcc, 1.0, v194, 1.0
	v_rcp_f32_e32 v202, v200
	s_nop 0
	v_fma_f32 v204, -v200, v202, 1.0
	v_fmac_f32_e32 v202, v204, v202
	v_mul_f32_e32 v203, v201, v202
	v_fma_f32 v204, -v200, v203, v201
	v_fmac_f32_e32 v203, v204, v202
	v_fma_f32 v204, -v200, v203, v201
	v_div_fmas_f32 v204, v204, v202, v203
	v_div_fixup_f32 v198, v204, v194, 1.0
	v_div_scale_f32 v200, s[8:9], v195, v195, 1.0
	v_div_scale_f32 v201, vcc, 1.0, v195, 1.0
	v_rcp_f32_e32 v202, v200
	s_nop 0
	v_fma_f32 v204, -v200, v202, 1.0
	v_fmac_f32_e32 v202, v204, v202
	v_mul_f32_e32 v203, v201, v202
	v_fma_f32 v204, -v200, v203, v201
	v_fmac_f32_e32 v203, v204, v202
	v_fma_f32 v204, -v200, v203, v201
	v_div_fmas_f32 v204, v204, v202, v203
	v_div_fixup_f32 v199, v204, v195, 1.0
	v_pk_mul_f32 v[196:197], v[188:189], v[196:197]
	v_pk_mul_f32 v[198:199], v[190:191], v[198:199]
	v_pk_mul_f32 v[196:197], v[184:185], v[196:197]
	v_pk_mul_f32 v[198:199], v[186:187], v[198:199]
	v_cvt_pk_bf16_f32 v206, v196, v197
	v_cvt_pk_bf16_f32 v207, v198, v199
	v_add_u32_e32 v152, 0x2c00, v152
	global_store_dwordx2 v152, v[206:207], s[18:19]
	v_lshlrev_b32_e32 v164, 16, v22
	v_and_b32_e32 v165, 0xffff0000, v22
	v_lshlrev_b32_e32 v166, 16, v23
	v_and_b32_e32 v167, 0xffff0000, v23
	v_lshlrev_b32_e32 v176, 16, v42
	v_and_b32_e32 v177, 0xffff0000, v42
	v_lshlrev_b32_e32 v178, 16, v43
	v_and_b32_e32 v179, 0xffff0000, v43
	v_pk_mul_f32 v[184:185], v[48:49], v[160:161]
	v_pk_mul_f32 v[188:189], v[64:65], v[172:173]
	v_pk_fma_f32 v[184:185], v[52:53], v[168:169], v[184:185]
	v_pk_fma_f32 v[188:189], v[68:69], v[180:181], v[188:189]
	v_pk_fma_f32 v[184:185], v[56:57], v[164:165], v[184:185]
	v_pk_fma_f32 v[188:189], v[72:73], v[176:177], v[188:189]
	v_pk_add_f32 v[184:185], v[184:185], v[60:61]
	v_pk_add_f32 v[188:189], v[188:189], v[76:77]
	v_pk_mul_f32 v[186:187], v[50:51], v[162:163]
	v_pk_mul_f32 v[190:191], v[66:67], v[174:175]
	v_pk_fma_f32 v[186:187], v[54:55], v[170:171], v[186:187]
	v_pk_fma_f32 v[190:191], v[70:71], v[182:183], v[190:191]
	v_pk_fma_f32 v[186:187], v[58:59], v[166:167], v[186:187]
	v_pk_fma_f32 v[190:191], v[74:75], v[178:179], v[190:191]
	v_pk_add_f32 v[186:187], v[186:187], v[62:63]
	v_pk_add_f32 v[190:191], v[190:191], v[78:79]
	v_mul_f32_e32 v192, 0xbfb8aa3b, v188
	v_mul_f32_e32 v193, 0xbfb8aa3b, v189
	v_mul_f32_e32 v194, 0xbfb8aa3b, v190
	v_mul_f32_e32 v195, 0xbfb8aa3b, v191
	v_exp_f32_e32 v192, v192
	v_exp_f32_e32 v193, v193
	v_exp_f32_e32 v194, v194
	v_exp_f32_e32 v195, v195
	s_nop 0
	v_pk_add_f32 v[192:193], v[192:193], 1.0 op_sel_hi:[1,0]
	v_pk_add_f32 v[194:195], v[194:195], 1.0 op_sel_hi:[1,0]
	v_div_scale_f32 v200, s[8:9], v192, v192, 1.0
	v_div_scale_f32 v201, vcc, 1.0, v192, 1.0
	v_rcp_f32_e32 v202, v200
	s_nop 0
	v_fma_f32 v204, -v200, v202, 1.0
	v_fmac_f32_e32 v202, v204, v202
	v_mul_f32_e32 v203, v201, v202
	v_fma_f32 v204, -v200, v203, v201
	v_fmac_f32_e32 v203, v204, v202
	v_fma_f32 v204, -v200, v203, v201
	v_div_fmas_f32 v204, v204, v202, v203
	v_div_fixup_f32 v196, v204, v192, 1.0
	v_div_scale_f32 v200, s[8:9], v193, v193, 1.0
	v_div_scale_f32 v201, vcc, 1.0, v193, 1.0
	v_rcp_f32_e32 v202, v200
	s_nop 0
	v_fma_f32 v204, -v200, v202, 1.0
	v_fmac_f32_e32 v202, v204, v202
	v_mul_f32_e32 v203, v201, v202
	v_fma_f32 v204, -v200, v203, v201
	v_fmac_f32_e32 v203, v204, v202
	v_fma_f32 v204, -v200, v203, v201
	v_div_fmas_f32 v204, v204, v202, v203
	v_div_fixup_f32 v197, v204, v193, 1.0
	v_div_scale_f32 v200, s[8:9], v194, v194, 1.0
	v_div_scale_f32 v201, vcc, 1.0, v194, 1.0
	v_rcp_f32_e32 v202, v200
	s_nop 0
	v_fma_f32 v204, -v200, v202, 1.0
	v_fmac_f32_e32 v202, v204, v202
	v_mul_f32_e32 v203, v201, v202
	v_fma_f32 v204, -v200, v203, v201
	v_fmac_f32_e32 v203, v204, v202
	v_fma_f32 v204, -v200, v203, v201
	v_div_fmas_f32 v204, v204, v202, v203
	v_div_fixup_f32 v198, v204, v194, 1.0
	v_div_scale_f32 v200, s[8:9], v195, v195, 1.0
	v_div_scale_f32 v201, vcc, 1.0, v195, 1.0
	v_rcp_f32_e32 v202, v200
	s_nop 0
	v_fma_f32 v204, -v200, v202, 1.0
	v_fmac_f32_e32 v202, v204, v202
	v_mul_f32_e32 v203, v201, v202
	v_fma_f32 v204, -v200, v203, v201
	v_fmac_f32_e32 v203, v204, v202
	v_fma_f32 v204, -v200, v203, v201
	v_div_fmas_f32 v204, v204, v202, v203
	v_div_fixup_f32 v199, v204, v195, 1.0
	v_pk_mul_f32 v[196:197], v[188:189], v[196:197]
	v_pk_mul_f32 v[198:199], v[190:191], v[198:199]
	v_pk_mul_f32 v[196:197], v[184:185], v[196:197]
	v_pk_mul_f32 v[198:199], v[186:187], v[198:199]
	v_cvt_pk_bf16_f32 v208, v196, v197
	v_cvt_pk_bf16_f32 v209, v198, v199
	v_add_u32_e32 v152, 0x2c00, v152
	global_store_dwordx2 v152, v[208:209], s[18:19]
	v_lshlrev_b32_e32 v168, 16, v24
	v_and_b32_e32 v169, 0xffff0000, v24
	v_lshlrev_b32_e32 v170, 16, v25
	v_and_b32_e32 v171, 0xffff0000, v25
	v_lshlrev_b32_e32 v180, 16, v44
	v_and_b32_e32 v181, 0xffff0000, v44
	v_lshlrev_b32_e32 v182, 16, v45
	v_and_b32_e32 v183, 0xffff0000, v45
	v_pk_mul_f32 v[184:185], v[48:49], v[164:165]
	v_pk_mul_f32 v[188:189], v[64:65], v[176:177]
	v_pk_fma_f32 v[184:185], v[52:53], v[160:161], v[184:185]
	v_pk_fma_f32 v[188:189], v[68:69], v[172:173], v[188:189]
	v_pk_fma_f32 v[184:185], v[56:57], v[168:169], v[184:185]
	v_pk_fma_f32 v[188:189], v[72:73], v[180:181], v[188:189]
	v_pk_add_f32 v[184:185], v[184:185], v[60:61]
	v_pk_add_f32 v[188:189], v[188:189], v[76:77]
	v_pk_mul_f32 v[186:187], v[50:51], v[166:167]
	v_pk_mul_f32 v[190:191], v[66:67], v[178:179]
	v_pk_fma_f32 v[186:187], v[54:55], v[162:163], v[186:187]
	v_pk_fma_f32 v[190:191], v[70:71], v[174:175], v[190:191]
	v_pk_fma_f32 v[186:187], v[58:59], v[170:171], v[186:187]
	v_pk_fma_f32 v[190:191], v[74:75], v[182:183], v[190:191]
	v_pk_add_f32 v[186:187], v[186:187], v[62:63]
	v_pk_add_f32 v[190:191], v[190:191], v[78:79]
	v_mul_f32_e32 v192, 0xbfb8aa3b, v188
	v_mul_f32_e32 v193, 0xbfb8aa3b, v189
	v_mul_f32_e32 v194, 0xbfb8aa3b, v190
	v_mul_f32_e32 v195, 0xbfb8aa3b, v191
	v_exp_f32_e32 v192, v192
	v_exp_f32_e32 v193, v193
	v_exp_f32_e32 v194, v194
	v_exp_f32_e32 v195, v195
	s_nop 0
	v_pk_add_f32 v[192:193], v[192:193], 1.0 op_sel_hi:[1,0]
	v_pk_add_f32 v[194:195], v[194:195], 1.0 op_sel_hi:[1,0]
	v_div_scale_f32 v200, s[8:9], v192, v192, 1.0
	v_div_scale_f32 v201, vcc, 1.0, v192, 1.0
	v_rcp_f32_e32 v202, v200
	s_nop 0
	v_fma_f32 v204, -v200, v202, 1.0
	v_fmac_f32_e32 v202, v204, v202
	v_mul_f32_e32 v203, v201, v202
	v_fma_f32 v204, -v200, v203, v201
	v_fmac_f32_e32 v203, v204, v202
	v_fma_f32 v204, -v200, v203, v201
	v_div_fmas_f32 v204, v204, v202, v203
	v_div_fixup_f32 v196, v204, v192, 1.0
	v_div_scale_f32 v200, s[8:9], v193, v193, 1.0
	v_div_scale_f32 v201, vcc, 1.0, v193, 1.0
	v_rcp_f32_e32 v202, v200
	s_nop 0
	v_fma_f32 v204, -v200, v202, 1.0
	v_fmac_f32_e32 v202, v204, v202
	v_mul_f32_e32 v203, v201, v202
	v_fma_f32 v204, -v200, v203, v201
	v_fmac_f32_e32 v203, v204, v202
	v_fma_f32 v204, -v200, v203, v201
	v_div_fmas_f32 v204, v204, v202, v203
	v_div_fixup_f32 v197, v204, v193, 1.0
	v_div_scale_f32 v200, s[8:9], v194, v194, 1.0
	v_div_scale_f32 v201, vcc, 1.0, v194, 1.0
	v_rcp_f32_e32 v202, v200
	s_nop 0
	v_fma_f32 v204, -v200, v202, 1.0
	v_fmac_f32_e32 v202, v204, v202
	v_mul_f32_e32 v203, v201, v202
	v_fma_f32 v204, -v200, v203, v201
	v_fmac_f32_e32 v203, v204, v202
	v_fma_f32 v204, -v200, v203, v201
	v_div_fmas_f32 v204, v204, v202, v203
	v_div_fixup_f32 v198, v204, v194, 1.0
	v_div_scale_f32 v200, s[8:9], v195, v195, 1.0
	v_div_scale_f32 v201, vcc, 1.0, v195, 1.0
	v_rcp_f32_e32 v202, v200
	s_nop 0
	v_fma_f32 v204, -v200, v202, 1.0
	v_fmac_f32_e32 v202, v204, v202
	v_mul_f32_e32 v203, v201, v202
	v_fma_f32 v204, -v200, v203, v201
	v_fmac_f32_e32 v203, v204, v202
	v_fma_f32 v204, -v200, v203, v201
	v_div_fmas_f32 v204, v204, v202, v203
	v_div_fixup_f32 v199, v204, v195, 1.0
	v_pk_mul_f32 v[196:197], v[188:189], v[196:197]
	v_pk_mul_f32 v[198:199], v[190:191], v[198:199]
	v_pk_mul_f32 v[196:197], v[184:185], v[196:197]
	v_pk_mul_f32 v[198:199], v[186:187], v[198:199]
	v_cvt_pk_bf16_f32 v206, v196, v197
	v_cvt_pk_bf16_f32 v207, v198, v199
	v_add_u32_e32 v152, 0x2c00, v152
	global_store_dwordx2 v152, v[206:207], s[18:19]
	v_lshlrev_b32_e32 v160, 16, v26
	v_and_b32_e32 v161, 0xffff0000, v26
	v_lshlrev_b32_e32 v162, 16, v27
	v_and_b32_e32 v163, 0xffff0000, v27
	v_lshlrev_b32_e32 v172, 16, v46
	v_and_b32_e32 v173, 0xffff0000, v46
	v_lshlrev_b32_e32 v174, 16, v47
	v_and_b32_e32 v175, 0xffff0000, v47
	v_pk_mul_f32 v[184:185], v[48:49], v[168:169]
	v_pk_mul_f32 v[188:189], v[64:65], v[180:181]
	v_pk_fma_f32 v[184:185], v[52:53], v[164:165], v[184:185]
	v_pk_fma_f32 v[188:189], v[68:69], v[176:177], v[188:189]
	v_pk_fma_f32 v[184:185], v[56:57], v[160:161], v[184:185]
	v_pk_fma_f32 v[188:189], v[72:73], v[172:173], v[188:189]
	v_pk_add_f32 v[184:185], v[184:185], v[60:61]
	v_pk_add_f32 v[188:189], v[188:189], v[76:77]
	v_pk_mul_f32 v[186:187], v[50:51], v[170:171]
	v_pk_mul_f32 v[190:191], v[66:67], v[182:183]
	v_pk_fma_f32 v[186:187], v[54:55], v[166:167], v[186:187]
	v_pk_fma_f32 v[190:191], v[70:71], v[178:179], v[190:191]
	v_pk_fma_f32 v[186:187], v[58:59], v[162:163], v[186:187]
	v_pk_fma_f32 v[190:191], v[74:75], v[174:175], v[190:191]
	v_pk_add_f32 v[186:187], v[186:187], v[62:63]
	v_pk_add_f32 v[190:191], v[190:191], v[78:79]
	v_mul_f32_e32 v192, 0xbfb8aa3b, v188
	v_mul_f32_e32 v193, 0xbfb8aa3b, v189
	v_mul_f32_e32 v194, 0xbfb8aa3b, v190
	v_mul_f32_e32 v195, 0xbfb8aa3b, v191
	v_exp_f32_e32 v192, v192
	v_exp_f32_e32 v193, v193
	v_exp_f32_e32 v194, v194
	v_exp_f32_e32 v195, v195
	s_nop 0
	v_pk_add_f32 v[192:193], v[192:193], 1.0 op_sel_hi:[1,0]
	v_pk_add_f32 v[194:195], v[194:195], 1.0 op_sel_hi:[1,0]
	v_div_scale_f32 v200, s[8:9], v192, v192, 1.0
	v_div_scale_f32 v201, vcc, 1.0, v192, 1.0
	v_rcp_f32_e32 v202, v200
	s_nop 0
	v_fma_f32 v204, -v200, v202, 1.0
	v_fmac_f32_e32 v202, v204, v202
	v_mul_f32_e32 v203, v201, v202
	v_fma_f32 v204, -v200, v203, v201
	v_fmac_f32_e32 v203, v204, v202
	v_fma_f32 v204, -v200, v203, v201
	v_div_fmas_f32 v204, v204, v202, v203
	v_div_fixup_f32 v196, v204, v192, 1.0
	v_div_scale_f32 v200, s[8:9], v193, v193, 1.0
	v_div_scale_f32 v201, vcc, 1.0, v193, 1.0
	v_rcp_f32_e32 v202, v200
	s_nop 0
	v_fma_f32 v204, -v200, v202, 1.0
	v_fmac_f32_e32 v202, v204, v202
	v_mul_f32_e32 v203, v201, v202
	v_fma_f32 v204, -v200, v203, v201
	v_fmac_f32_e32 v203, v204, v202
	v_fma_f32 v204, -v200, v203, v201
	v_div_fmas_f32 v204, v204, v202, v203
	v_div_fixup_f32 v197, v204, v193, 1.0
	v_div_scale_f32 v200, s[8:9], v194, v194, 1.0
	v_div_scale_f32 v201, vcc, 1.0, v194, 1.0
	v_rcp_f32_e32 v202, v200
	s_nop 0
	v_fma_f32 v204, -v200, v202, 1.0
	v_fmac_f32_e32 v202, v204, v202
	v_mul_f32_e32 v203, v201, v202
	v_fma_f32 v204, -v200, v203, v201
	v_fmac_f32_e32 v203, v204, v202
	v_fma_f32 v204, -v200, v203, v201
	v_div_fmas_f32 v204, v204, v202, v203
	v_div_fixup_f32 v198, v204, v194, 1.0
	v_div_scale_f32 v200, s[8:9], v195, v195, 1.0
	v_div_scale_f32 v201, vcc, 1.0, v195, 1.0
	v_rcp_f32_e32 v202, v200
	s_nop 0
	v_fma_f32 v204, -v200, v202, 1.0
	v_fmac_f32_e32 v202, v204, v202
	v_mul_f32_e32 v203, v201, v202
	v_fma_f32 v204, -v200, v203, v201
	v_fmac_f32_e32 v203, v204, v202
	v_fma_f32 v204, -v200, v203, v201
	v_div_fmas_f32 v204, v204, v202, v203
	v_div_fixup_f32 v199, v204, v195, 1.0
	v_pk_mul_f32 v[196:197], v[188:189], v[196:197]
	v_pk_mul_f32 v[198:199], v[190:191], v[198:199]
	v_pk_mul_f32 v[196:197], v[184:185], v[196:197]
	v_pk_mul_f32 v[198:199], v[186:187], v[198:199]
	v_cvt_pk_bf16_f32 v208, v196, v197
	v_cvt_pk_bf16_f32 v209, v198, v199
	v_add_u32_e32 v152, 0x2c00, v152
	global_store_dwordx2 v152, v[208:209], s[18:19]
	s_mov_b64 exec, s[38:39]
	s_mov_b32 s38, 0x2e8ba2e9
	s_mov_b32 s39, 0x160000
	s_cbranch_execz .Lcv_done
	v_add_u32_e32 v154, s3, v158
	v_cmp_gt_u32_e32 vcc, s39, v154
	s_and_b64 s[8:9], vcc, exec
	s_nop 0
	v_cndmask_b32_e32 v218, v158, v154, vcc
	v_mul_hi_u32 v2, v218, s38
	v_lshrrev_b32_e32 v2, 8, v2
	v_mul_u32_u24_e32 v3, 0x580, v2
	v_sub_u32_e32 v3, v218, v3
	v_lshlrev_b32_e32 v4, 3, v3
	v_and_b32_e32 v5, 0x1ff, v2
	v_cmp_eq_u32_e32 vcc, 0, v5
	s_nop 1
	v_cndmask_b32_e64 v153, 0, 1, vcc
	v_lshlrev_b32_e32 v5, 3, v2
	v_mul_u32_u24_e32 v6, 0x2c00, v5
	v_add_u32_e32 v152, v6, v4
	v_mul_u32_u24_e32 v6, 0x5800, v5
	v_add_u32_e32 v6, v6, v4
	v_add_u32_e32 v7, 0xffff5000, v6
	v_cndmask_b32_e32 v7, v7, v6, vcc
	global_load_dwordx2 v[8:9], v7, s[14:15]
	global_load_dwordx2 v[28:29], v7, s[16:17]
	v_add_u32_e32 v7, 0xffffa800, v6
	v_cndmask_b32_e32 v7, v7, v6, vcc
	global_load_dwordx2 v[10:11], v7, s[14:15]
	global_load_dwordx2 v[30:31], v7, s[16:17]
	global_load_dwordx2 v[12:13], v6, s[14:15]
	global_load_dwordx2 v[32:33], v6, s[16:17]
	v_add_u32_e32 v6, 0x5800, v6
	global_load_dwordx2 v[14:15], v6, s[14:15]
	global_load_dwordx2 v[34:35], v6, s[16:17]
	v_add_u32_e32 v6, 0x5800, v6
	global_load_dwordx2 v[16:17], v6, s[14:15]
	global_load_dwordx2 v[36:37], v6, s[16:17]
	v_add_u32_e32 v6, 0x5800, v6
	global_load_dwordx2 v[18:19], v6, s[14:15]
	global_load_dwordx2 v[38:39], v6, s[16:17]
	v_add_u32_e32 v6, 0x5800, v6
	global_load_dwordx2 v[20:21], v6, s[14:15]
	global_load_dwordx2 v[40:41], v6, s[16:17]
	v_add_u32_e32 v6, 0x5800, v6
	global_load_dwordx2 v[22:23], v6, s[14:15]
	global_load_dwordx2 v[42:43], v6, s[16:17]
	v_add_u32_e32 v6, 0x5800, v6
	global_load_dwordx2 v[24:25], v6, s[14:15]
	global_load_dwordx2 v[44:45], v6, s[16:17]
	v_add_u32_e32 v6, 0x5800, v6
	global_load_dwordx2 v[26:27], v6, s[14:15]
	global_load_dwordx2 v[46:47], v6, s[16:17]
	v_lshlrev_b32_e32 v4, 4, v3
	global_load_dwordx4 v[48:51], v4, s[20:21]
	global_load_dwordx4 v[52:55], v4, s[22:23]
	global_load_dwordx4 v[56:59], v4, s[24:25]
	global_load_dwordx4 v[60:63], v4, s[56:57]
	global_load_dwordx4 v[64:67], v4, s[26:27]
	global_load_dwordx4 v[68:71], v4, s[28:29]
	global_load_dwordx4 v[72:75], v4, s[30:31]
	global_load_dwordx4 v[76:79], v4, s[36:37]
	s_mov_b64 s[38:39], s[8:9]
	s_waitcnt vmcnt(36)
	v_cmp_ne_u32_e32 vcc, 0, v157
	s_nop 1
	v_cndmask_b32_e32 v80, v80, v216, vcc
	v_cndmask_b32_e32 v81, v81, v216, vcc
	v_cndmask_b32_e32 v82, v82, v216, vcc
	v_cndmask_b32_e32 v83, v83, v216, vcc
	v_cndmask_b32_e32 v100, v100, v216, vcc
	v_cndmask_b32_e32 v101, v101, v216, vcc
	v_cndmask_b32_e32 v102, v102, v216, vcc
	v_cndmask_b32_e32 v103, v103, v216, vcc
	v_lshlrev_b32_e32 v160, 16, v80
	v_and_b32_e32 v161, 0xffff0000, v80
	v_lshlrev_b32_e32 v162, 16, v81
	v_and_b32_e32 v163, 0xffff0000, v81
	v_lshlrev_b32_e32 v172, 16, v100
	v_and_b32_e32 v173, 0xffff0000, v100
	v_lshlrev_b32_e32 v174, 16, v101
	v_and_b32_e32 v175, 0xffff0000, v101
	v_lshlrev_b32_e32 v164, 16, v82
	v_and_b32_e32 v165, 0xffff0000, v82
	v_lshlrev_b32_e32 v166, 16, v83
	v_and_b32_e32 v167, 0xffff0000, v83
	v_lshlrev_b32_e32 v176, 16, v102
	v_and_b32_e32 v177, 0xffff0000, v102
	v_lshlrev_b32_e32 v178, 16, v103
	v_and_b32_e32 v179, 0xffff0000, v103
	v_lshlrev_b32_e32 v168, 16, v84
	v_and_b32_e32 v169, 0xffff0000, v84
	v_lshlrev_b32_e32 v170, 16, v85
	v_and_b32_e32 v171, 0xffff0000, v85
	v_lshlrev_b32_e32 v180, 16, v104
	v_and_b32_e32 v181, 0xffff0000, v104
	v_lshlrev_b32_e32 v182, 16, v105
	v_and_b32_e32 v183, 0xffff0000, v105
	v_pk_mul_f32 v[184:185], v[120:121], v[164:165]
	v_pk_mul_f32 v[188:189], v[136:137], v[176:177]
	v_pk_fma_f32 v[184:185], v[124:125], v[160:161], v[184:185]
	v_pk_fma_f32 v[188:189], v[140:141], v[172:173], v[188:189]
	v_pk_fma_f32 v[184:185], v[128:129], v[168:169], v[184:185]
	v_pk_fma_f32 v[188:189], v[144:145], v[180:181], v[188:189]
	v_pk_add_f32 v[184:185], v[184:185], v[132:133]
	v_pk_add_f32 v[188:189], v[188:189], v[148:149]
	v_pk_mul_f32 v[186:187], v[122:123], v[166:167]
	v_pk_mul_f32 v[190:191], v[138:139], v[178:179]
	v_pk_fma_f32 v[186:187], v[126:127], v[162:163], v[186:187]
	v_pk_fma_f32 v[190:191], v[142:143], v[174:175], v[190:191]
	v_pk_fma_f32 v[186:187], v[130:131], v[170:171], v[186:187]
	v_pk_fma_f32 v[190:191], v[146:147], v[182:183], v[190:191]
	v_pk_add_f32 v[186:187], v[186:187], v[134:135]
	v_pk_add_f32 v[190:191], v[190:191], v[150:151]
	v_mul_f32_e32 v192, 0xbfb8aa3b, v188
	v_mul_f32_e32 v193, 0xbfb8aa3b, v189
	v_mul_f32_e32 v194, 0xbfb8aa3b, v190
	v_mul_f32_e32 v195, 0xbfb8aa3b, v191
	v_exp_f32_e32 v192, v192
	v_exp_f32_e32 v193, v193
	v_exp_f32_e32 v194, v194
	v_exp_f32_e32 v195, v195
	s_nop 0
	v_pk_add_f32 v[192:193], v[192:193], 1.0 op_sel_hi:[1,0]
	v_pk_add_f32 v[194:195], v[194:195], 1.0 op_sel_hi:[1,0]
	v_div_scale_f32 v200, s[8:9], v192, v192, 1.0
	v_div_scale_f32 v201, vcc, 1.0, v192, 1.0
	v_rcp_f32_e32 v202, v200
	s_nop 0
	v_fma_f32 v204, -v200, v202, 1.0
	v_fmac_f32_e32 v202, v204, v202
	v_mul_f32_e32 v203, v201, v202
	v_fma_f32 v204, -v200, v203, v201
	v_fmac_f32_e32 v203, v204, v202
	v_fma_f32 v204, -v200, v203, v201
	v_div_fmas_f32 v204, v204, v202, v203
	v_div_fixup_f32 v196, v204, v192, 1.0
	v_div_scale_f32 v200, s[8:9], v193, v193, 1.0
	v_div_scale_f32 v201, vcc, 1.0, v193, 1.0
	v_rcp_f32_e32 v202, v200
	s_nop 0
	v_fma_f32 v204, -v200, v202, 1.0
	v_fmac_f32_e32 v202, v204, v202
	v_mul_f32_e32 v203, v201, v202
	v_fma_f32 v204, -v200, v203, v201
	v_fmac_f32_e32 v203, v204, v202
	v_fma_f32 v204, -v200, v203, v201
	v_div_fmas_f32 v204, v204, v202, v203
	v_div_fixup_f32 v197, v204, v193, 1.0
	v_div_scale_f32 v200, s[8:9], v194, v194, 1.0
	v_div_scale_f32 v201, vcc, 1.0, v194, 1.0
	v_rcp_f32_e32 v202, v200
	s_nop 0
	v_fma_f32 v204, -v200, v202, 1.0
	v_fmac_f32_e32 v202, v204, v202
	v_mul_f32_e32 v203, v201, v202
	v_fma_f32 v204, -v200, v203, v201
	v_fmac_f32_e32 v203, v204, v202
	v_fma_f32 v204, -v200, v203, v201
	v_div_fmas_f32 v204, v204, v202, v203
	v_div_fixup_f32 v198, v204, v194, 1.0
	v_div_scale_f32 v200, s[8:9], v195, v195, 1.0
	v_div_scale_f32 v201, vcc, 1.0, v195, 1.0
	v_rcp_f32_e32 v202, v200
	s_nop 0
	v_fma_f32 v204, -v200, v202, 1.0
	v_fmac_f32_e32 v202, v204, v202
	v_mul_f32_e32 v203, v201, v202
	v_fma_f32 v204, -v200, v203, v201
	v_fmac_f32_e32 v203, v204, v202
	v_fma_f32 v204, -v200, v203, v201
	v_div_fmas_f32 v204, v204, v202, v203
	v_div_fixup_f32 v199, v204, v195, 1.0
	v_pk_mul_f32 v[196:197], v[188:189], v[196:197]
	v_pk_mul_f32 v[198:199], v[190:191], v[198:199]
	v_pk_mul_f32 v[196:197], v[184:185], v[196:197]
	v_pk_mul_f32 v[198:199], v[186:187], v[198:199]
	v_cvt_pk_bf16_f32 v206, v196, v197
	v_cvt_pk_bf16_f32 v207, v198, v199
	global_store_dwordx2 v156, v[206:207], s[18:19]
	v_lshlrev_b32_e32 v160, 16, v86
	v_and_b32_e32 v161, 0xffff0000, v86
	v_lshlrev_b32_e32 v162, 16, v87
	v_and_b32_e32 v163, 0xffff0000, v87
	v_lshlrev_b32_e32 v172, 16, v106
	v_and_b32_e32 v173, 0xffff0000, v106
	v_lshlrev_b32_e32 v174, 16, v107
	v_and_b32_e32 v175, 0xffff0000, v107
	v_pk_mul_f32 v[184:185], v[120:121], v[168:169]
	v_pk_mul_f32 v[188:189], v[136:137], v[180:181]
	v_pk_fma_f32 v[184:185], v[124:125], v[164:165], v[184:185]
	v_pk_fma_f32 v[188:189], v[140:141], v[176:177], v[188:189]
	v_pk_fma_f32 v[184:185], v[128:129], v[160:161], v[184:185]
	v_pk_fma_f32 v[188:189], v[144:145], v[172:173], v[188:189]
	v_pk_add_f32 v[184:185], v[184:185], v[132:133]
	v_pk_add_f32 v[188:189], v[188:189], v[148:149]
	v_pk_mul_f32 v[186:187], v[122:123], v[170:171]
	v_pk_mul_f32 v[190:191], v[138:139], v[182:183]
	v_pk_fma_f32 v[186:187], v[126:127], v[166:167], v[186:187]
	v_pk_fma_f32 v[190:191], v[142:143], v[178:179], v[190:191]
	v_pk_fma_f32 v[186:187], v[130:131], v[162:163], v[186:187]
	v_pk_fma_f32 v[190:191], v[146:147], v[174:175], v[190:191]
	v_pk_add_f32 v[186:187], v[186:187], v[134:135]
	v_pk_add_f32 v[190:191], v[190:191], v[150:151]
	v_mul_f32_e32 v192, 0xbfb8aa3b, v188
	v_mul_f32_e32 v193, 0xbfb8aa3b, v189
	v_mul_f32_e32 v194, 0xbfb8aa3b, v190
	v_mul_f32_e32 v195, 0xbfb8aa3b, v191
	v_exp_f32_e32 v192, v192
	v_exp_f32_e32 v193, v193
	v_exp_f32_e32 v194, v194
	v_exp_f32_e32 v195, v195
	s_nop 0
	v_pk_add_f32 v[192:193], v[192:193], 1.0 op_sel_hi:[1,0]
	v_pk_add_f32 v[194:195], v[194:195], 1.0 op_sel_hi:[1,0]
	v_div_scale_f32 v200, s[8:9], v192, v192, 1.0
	v_div_scale_f32 v201, vcc, 1.0, v192, 1.0
	v_rcp_f32_e32 v202, v200
	s_nop 0
	v_fma_f32 v204, -v200, v202, 1.0
	v_fmac_f32_e32 v202, v204, v202
	v_mul_f32_e32 v203, v201, v202
	v_fma_f32 v204, -v200, v203, v201
	v_fmac_f32_e32 v203, v204, v202
	v_fma_f32 v204, -v200, v203, v201
	v_div_fmas_f32 v204, v204, v202, v203
	v_div_fixup_f32 v196, v204, v192, 1.0
	v_div_scale_f32 v200, s[8:9], v193, v193, 1.0
	v_div_scale_f32 v201, vcc, 1.0, v193, 1.0
	v_rcp_f32_e32 v202, v200
	s_nop 0
	v_fma_f32 v204, -v200, v202, 1.0
	v_fmac_f32_e32 v202, v204, v202
	v_mul_f32_e32 v203, v201, v202
	v_fma_f32 v204, -v200, v203, v201
	v_fmac_f32_e32 v203, v204, v202
	v_fma_f32 v204, -v200, v203, v201
	v_div_fmas_f32 v204, v204, v202, v203
	v_div_fixup_f32 v197, v204, v193, 1.0
	v_div_scale_f32 v200, s[8:9], v194, v194, 1.0
	v_div_scale_f32 v201, vcc, 1.0, v194, 1.0
	v_rcp_f32_e32 v202, v200
	s_nop 0
	v_fma_f32 v204, -v200, v202, 1.0
	v_fmac_f32_e32 v202, v204, v202
	v_mul_f32_e32 v203, v201, v202
	v_fma_f32 v204, -v200, v203, v201
	v_fmac_f32_e32 v203, v204, v202
	v_fma_f32 v204, -v200, v203, v201
	v_div_fmas_f32 v204, v204, v202, v203
	v_div_fixup_f32 v198, v204, v194, 1.0
	v_div_scale_f32 v200, s[8:9], v195, v195, 1.0
	v_div_scale_f32 v201, vcc, 1.0, v195, 1.0
	v_rcp_f32_e32 v202, v200
	s_nop 0
	v_fma_f32 v204, -v200, v202, 1.0
	v_fmac_f32_e32 v202, v204, v202
	v_mul_f32_e32 v203, v201, v202
	v_fma_f32 v204, -v200, v203, v201
	v_fmac_f32_e32 v203, v204, v202
	v_fma_f32 v204, -v200, v203, v201
	v_div_fmas_f32 v204, v204, v202, v203
	v_div_fixup_f32 v199, v204, v195, 1.0
	v_pk_mul_f32 v[196:197], v[188:189], v[196:197]
	v_pk_mul_f32 v[198:199], v[190:191], v[198:199]
	v_pk_mul_f32 v[196:197], v[184:185], v[196:197]
	v_pk_mul_f32 v[198:199], v[186:187], v[198:199]
	v_cvt_pk_bf16_f32 v208, v196, v197
	v_cvt_pk_bf16_f32 v209, v198, v199
	v_add_u32_e32 v156, 0x2c00, v156
	global_store_dwordx2 v156, v[208:209], s[18:19]
	v_lshlrev_b32_e32 v164, 16, v88
	v_and_b32_e32 v165, 0xffff0000, v88
	v_lshlrev_b32_e32 v166, 16, v89
	v_and_b32_e32 v167, 0xffff0000, v89
	v_lshlrev_b32_e32 v176, 16, v108
	v_and_b32_e32 v177, 0xffff0000, v108
	v_lshlrev_b32_e32 v178, 16, v109
	v_and_b32_e32 v179, 0xffff0000, v109
	v_pk_mul_f32 v[184:185], v[120:121], v[160:161]
	v_pk_mul_f32 v[188:189], v[136:137], v[172:173]
	v_pk_fma_f32 v[184:185], v[124:125], v[168:169], v[184:185]
	v_pk_fma_f32 v[188:189], v[140:141], v[180:181], v[188:189]
	v_pk_fma_f32 v[184:185], v[128:129], v[164:165], v[184:185]
	v_pk_fma_f32 v[188:189], v[144:145], v[176:177], v[188:189]
	v_pk_add_f32 v[184:185], v[184:185], v[132:133]
	v_pk_add_f32 v[188:189], v[188:189], v[148:149]
	v_pk_mul_f32 v[186:187], v[122:123], v[162:163]
	v_pk_mul_f32 v[190:191], v[138:139], v[174:175]
	v_pk_fma_f32 v[186:187], v[126:127], v[170:171], v[186:187]
	v_pk_fma_f32 v[190:191], v[142:143], v[182:183], v[190:191]
	v_pk_fma_f32 v[186:187], v[130:131], v[166:167], v[186:187]
	v_pk_fma_f32 v[190:191], v[146:147], v[178:179], v[190:191]
	v_pk_add_f32 v[186:187], v[186:187], v[134:135]
	v_pk_add_f32 v[190:191], v[190:191], v[150:151]
	v_mul_f32_e32 v192, 0xbfb8aa3b, v188
	v_mul_f32_e32 v193, 0xbfb8aa3b, v189
	v_mul_f32_e32 v194, 0xbfb8aa3b, v190
	v_mul_f32_e32 v195, 0xbfb8aa3b, v191
	v_exp_f32_e32 v192, v192
	v_exp_f32_e32 v193, v193
	v_exp_f32_e32 v194, v194
	v_exp_f32_e32 v195, v195
	s_nop 0
	v_pk_add_f32 v[192:193], v[192:193], 1.0 op_sel_hi:[1,0]
	v_pk_add_f32 v[194:195], v[194:195], 1.0 op_sel_hi:[1,0]
	v_div_scale_f32 v200, s[8:9], v192, v192, 1.0
	v_div_scale_f32 v201, vcc, 1.0, v192, 1.0
	v_rcp_f32_e32 v202, v200
	s_nop 0
	v_fma_f32 v204, -v200, v202, 1.0
	v_fmac_f32_e32 v202, v204, v202
	v_mul_f32_e32 v203, v201, v202
	v_fma_f32 v204, -v200, v203, v201
	v_fmac_f32_e32 v203, v204, v202
	v_fma_f32 v204, -v200, v203, v201
	v_div_fmas_f32 v204, v204, v202, v203
	v_div_fixup_f32 v196, v204, v192, 1.0
	v_div_scale_f32 v200, s[8:9], v193, v193, 1.0
	v_div_scale_f32 v201, vcc, 1.0, v193, 1.0
	v_rcp_f32_e32 v202, v200
	s_nop 0
	v_fma_f32 v204, -v200, v202, 1.0
	v_fmac_f32_e32 v202, v204, v202
	v_mul_f32_e32 v203, v201, v202
	v_fma_f32 v204, -v200, v203, v201
	v_fmac_f32_e32 v203, v204, v202
	v_fma_f32 v204, -v200, v203, v201
	v_div_fmas_f32 v204, v204, v202, v203
	v_div_fixup_f32 v197, v204, v193, 1.0
	v_div_scale_f32 v200, s[8:9], v194, v194, 1.0
	v_div_scale_f32 v201, vcc, 1.0, v194, 1.0
	v_rcp_f32_e32 v202, v200
	s_nop 0
	v_fma_f32 v204, -v200, v202, 1.0
	v_fmac_f32_e32 v202, v204, v202
	v_mul_f32_e32 v203, v201, v202
	v_fma_f32 v204, -v200, v203, v201
	v_fmac_f32_e32 v203, v204, v202
	v_fma_f32 v204, -v200, v203, v201
	v_div_fmas_f32 v204, v204, v202, v203
	v_div_fixup_f32 v198, v204, v194, 1.0
	v_div_scale_f32 v200, s[8:9], v195, v195, 1.0
	v_div_scale_f32 v201, vcc, 1.0, v195, 1.0
	v_rcp_f32_e32 v202, v200
	s_nop 0
	v_fma_f32 v204, -v200, v202, 1.0
	v_fmac_f32_e32 v202, v204, v202
	v_mul_f32_e32 v203, v201, v202
	v_fma_f32 v204, -v200, v203, v201
	v_fmac_f32_e32 v203, v204, v202
	v_fma_f32 v204, -v200, v203, v201
	v_div_fmas_f32 v204, v204, v202, v203
	v_div_fixup_f32 v199, v204, v195, 1.0
	v_pk_mul_f32 v[196:197], v[188:189], v[196:197]
	v_pk_mul_f32 v[198:199], v[190:191], v[198:199]
	v_pk_mul_f32 v[196:197], v[184:185], v[196:197]
	v_pk_mul_f32 v[198:199], v[186:187], v[198:199]
	v_cvt_pk_bf16_f32 v206, v196, v197
	v_cvt_pk_bf16_f32 v207, v198, v199
	v_add_u32_e32 v156, 0x2c00, v156
	global_store_dwordx2 v156, v[206:207], s[18:19]
	v_lshlrev_b32_e32 v168, 16, v90
	v_and_b32_e32 v169, 0xffff0000, v90
	v_lshlrev_b32_e32 v170, 16, v91
	v_and_b32_e32 v171, 0xffff0000, v91
	v_lshlrev_b32_e32 v180, 16, v110
	v_and_b32_e32 v181, 0xffff0000, v110
	v_lshlrev_b32_e32 v182, 16, v111
	v_and_b32_e32 v183, 0xffff0000, v111
	v_pk_mul_f32 v[184:185], v[120:121], v[164:165]
	v_pk_mul_f32 v[188:189], v[136:137], v[176:177]
	v_pk_fma_f32 v[184:185], v[124:125], v[160:161], v[184:185]
	v_pk_fma_f32 v[188:189], v[140:141], v[172:173], v[188:189]
	v_pk_fma_f32 v[184:185], v[128:129], v[168:169], v[184:185]
	v_pk_fma_f32 v[188:189], v[144:145], v[180:181], v[188:189]
	v_pk_add_f32 v[184:185], v[184:185], v[132:133]
	v_pk_add_f32 v[188:189], v[188:189], v[148:149]
	v_pk_mul_f32 v[186:187], v[122:123], v[166:167]
	v_pk_mul_f32 v[190:191], v[138:139], v[178:179]
	v_pk_fma_f32 v[186:187], v[126:127], v[162:163], v[186:187]
	v_pk_fma_f32 v[190:191], v[142:143], v[174:175], v[190:191]
	v_pk_fma_f32 v[186:187], v[130:131], v[170:171], v[186:187]
	v_pk_fma_f32 v[190:191], v[146:147], v[182:183], v[190:191]
	v_pk_add_f32 v[186:187], v[186:187], v[134:135]
	v_pk_add_f32 v[190:191], v[190:191], v[150:151]
	v_mul_f32_e32 v192, 0xbfb8aa3b, v188
	v_mul_f32_e32 v193, 0xbfb8aa3b, v189
	v_mul_f32_e32 v194, 0xbfb8aa3b, v190
	v_mul_f32_e32 v195, 0xbfb8aa3b, v191
	v_exp_f32_e32 v192, v192
	v_exp_f32_e32 v193, v193
	v_exp_f32_e32 v194, v194
	v_exp_f32_e32 v195, v195
	s_nop 0
	v_pk_add_f32 v[192:193], v[192:193], 1.0 op_sel_hi:[1,0]
	v_pk_add_f32 v[194:195], v[194:195], 1.0 op_sel_hi:[1,0]
	v_div_scale_f32 v200, s[8:9], v192, v192, 1.0
	v_div_scale_f32 v201, vcc, 1.0, v192, 1.0
	v_rcp_f32_e32 v202, v200
	s_nop 0
	v_fma_f32 v204, -v200, v202, 1.0
	v_fmac_f32_e32 v202, v204, v202
	v_mul_f32_e32 v203, v201, v202
	v_fma_f32 v204, -v200, v203, v201
	v_fmac_f32_e32 v203, v204, v202
	v_fma_f32 v204, -v200, v203, v201
	v_div_fmas_f32 v204, v204, v202, v203
	v_div_fixup_f32 v196, v204, v192, 1.0
	v_div_scale_f32 v200, s[8:9], v193, v193, 1.0
	v_div_scale_f32 v201, vcc, 1.0, v193, 1.0
	v_rcp_f32_e32 v202, v200
	s_nop 0
	v_fma_f32 v204, -v200, v202, 1.0
	v_fmac_f32_e32 v202, v204, v202
	v_mul_f32_e32 v203, v201, v202
	v_fma_f32 v204, -v200, v203, v201
	v_fmac_f32_e32 v203, v204, v202
	v_fma_f32 v204, -v200, v203, v201
	v_div_fmas_f32 v204, v204, v202, v203
	v_div_fixup_f32 v197, v204, v193, 1.0
	v_div_scale_f32 v200, s[8:9], v194, v194, 1.0
	v_div_scale_f32 v201, vcc, 1.0, v194, 1.0
	v_rcp_f32_e32 v202, v200
	s_nop 0
	v_fma_f32 v204, -v200, v202, 1.0
	v_fmac_f32_e32 v202, v204, v202
	v_mul_f32_e32 v203, v201, v202
	v_fma_f32 v204, -v200, v203, v201
	v_fmac_f32_e32 v203, v204, v202
	v_fma_f32 v204, -v200, v203, v201
	v_div_fmas_f32 v204, v204, v202, v203
	v_div_fixup_f32 v198, v204, v194, 1.0
	v_div_scale_f32 v200, s[8:9], v195, v195, 1.0
	v_div_scale_f32 v201, vcc, 1.0, v195, 1.0
	v_rcp_f32_e32 v202, v200
	s_nop 0
	v_fma_f32 v204, -v200, v202, 1.0
	v_fmac_f32_e32 v202, v204, v202
	v_mul_f32_e32 v203, v201, v202
	v_fma_f32 v204, -v200, v203, v201
	v_fmac_f32_e32 v203, v204, v202
	v_fma_f32 v204, -v200, v203, v201
	v_div_fmas_f32 v204, v204, v202, v203
	v_div_fixup_f32 v199, v204, v195, 1.0
	v_pk_mul_f32 v[196:197], v[188:189], v[196:197]
	v_pk_mul_f32 v[198:199], v[190:191], v[198:199]
	v_pk_mul_f32 v[196:197], v[184:185], v[196:197]
	v_pk_mul_f32 v[198:199], v[186:187], v[198:199]
	v_cvt_pk_bf16_f32 v208, v196, v197
	v_cvt_pk_bf16_f32 v209, v198, v199
	v_add_u32_e32 v156, 0x2c00, v156
	global_store_dwordx2 v156, v[208:209], s[18:19]
	v_lshlrev_b32_e32 v160, 16, v92
	v_and_b32_e32 v161, 0xffff0000, v92
	v_lshlrev_b32_e32 v162, 16, v93
	v_and_b32_e32 v163, 0xffff0000, v93
	v_lshlrev_b32_e32 v172, 16, v112
	v_and_b32_e32 v173, 0xffff0000, v112
	v_lshlrev_b32_e32 v174, 16, v113
	v_and_b32_e32 v175, 0xffff0000, v113
	v_pk_mul_f32 v[184:185], v[120:121], v[168:169]
	v_pk_mul_f32 v[188:189], v[136:137], v[180:181]
	v_pk_fma_f32 v[184:185], v[124:125], v[164:165], v[184:185]
	v_pk_fma_f32 v[188:189], v[140:141], v[176:177], v[188:189]
	v_pk_fma_f32 v[184:185], v[128:129], v[160:161], v[184:185]
	v_pk_fma_f32 v[188:189], v[144:145], v[172:173], v[188:189]
	v_pk_add_f32 v[184:185], v[184:185], v[132:133]
	v_pk_add_f32 v[188:189], v[188:189], v[148:149]
	v_pk_mul_f32 v[186:187], v[122:123], v[170:171]
	v_pk_mul_f32 v[190:191], v[138:139], v[182:183]
	v_pk_fma_f32 v[186:187], v[126:127], v[166:167], v[186:187]
	v_pk_fma_f32 v[190:191], v[142:143], v[178:179], v[190:191]
	v_pk_fma_f32 v[186:187], v[130:131], v[162:163], v[186:187]
	v_pk_fma_f32 v[190:191], v[146:147], v[174:175], v[190:191]
	v_pk_add_f32 v[186:187], v[186:187], v[134:135]
	v_pk_add_f32 v[190:191], v[190:191], v[150:151]
	v_mul_f32_e32 v192, 0xbfb8aa3b, v188
	v_mul_f32_e32 v193, 0xbfb8aa3b, v189
	v_mul_f32_e32 v194, 0xbfb8aa3b, v190
	v_mul_f32_e32 v195, 0xbfb8aa3b, v191
	v_exp_f32_e32 v192, v192
	v_exp_f32_e32 v193, v193
	v_exp_f32_e32 v194, v194
	v_exp_f32_e32 v195, v195
	s_nop 0
	v_pk_add_f32 v[192:193], v[192:193], 1.0 op_sel_hi:[1,0]
	v_pk_add_f32 v[194:195], v[194:195], 1.0 op_sel_hi:[1,0]
	v_div_scale_f32 v200, s[8:9], v192, v192, 1.0
	v_div_scale_f32 v201, vcc, 1.0, v192, 1.0
	v_rcp_f32_e32 v202, v200
	s_nop 0
	v_fma_f32 v204, -v200, v202, 1.0
	v_fmac_f32_e32 v202, v204, v202
	v_mul_f32_e32 v203, v201, v202
	v_fma_f32 v204, -v200, v203, v201
	v_fmac_f32_e32 v203, v204, v202
	v_fma_f32 v204, -v200, v203, v201
	v_div_fmas_f32 v204, v204, v202, v203
	v_div_fixup_f32 v196, v204, v192, 1.0
	v_div_scale_f32 v200, s[8:9], v193, v193, 1.0
	v_div_scale_f32 v201, vcc, 1.0, v193, 1.0
	v_rcp_f32_e32 v202, v200
	s_nop 0
	v_fma_f32 v204, -v200, v202, 1.0
	v_fmac_f32_e32 v202, v204, v202
	v_mul_f32_e32 v203, v201, v202
	v_fma_f32 v204, -v200, v203, v201
	v_fmac_f32_e32 v203, v204, v202
	v_fma_f32 v204, -v200, v203, v201
	v_div_fmas_f32 v204, v204, v202, v203
	v_div_fixup_f32 v197, v204, v193, 1.0
	v_div_scale_f32 v200, s[8:9], v194, v194, 1.0
	v_div_scale_f32 v201, vcc, 1.0, v194, 1.0
	v_rcp_f32_e32 v202, v200
	s_nop 0
	v_fma_f32 v204, -v200, v202, 1.0
	v_fmac_f32_e32 v202, v204, v202
	v_mul_f32_e32 v203, v201, v202
	v_fma_f32 v204, -v200, v203, v201
	v_fmac_f32_e32 v203, v204, v202
	v_fma_f32 v204, -v200, v203, v201
	v_div_fmas_f32 v204, v204, v202, v203
	v_div_fixup_f32 v198, v204, v194, 1.0
	v_div_scale_f32 v200, s[8:9], v195, v195, 1.0
	v_div_scale_f32 v201, vcc, 1.0, v195, 1.0
	v_rcp_f32_e32 v202, v200
	s_nop 0
	v_fma_f32 v204, -v200, v202, 1.0
	v_fmac_f32_e32 v202, v204, v202
	v_mul_f32_e32 v203, v201, v202
	v_fma_f32 v204, -v200, v203, v201
	v_fmac_f32_e32 v203, v204, v202
	v_fma_f32 v204, -v200, v203, v201
	v_div_fmas_f32 v204, v204, v202, v203
	v_div_fixup_f32 v199, v204, v195, 1.0
	v_pk_mul_f32 v[196:197], v[188:189], v[196:197]
	v_pk_mul_f32 v[198:199], v[190:191], v[198:199]
	v_pk_mul_f32 v[196:197], v[184:185], v[196:197]
	v_pk_mul_f32 v[198:199], v[186:187], v[198:199]
	v_cvt_pk_bf16_f32 v206, v196, v197
	v_cvt_pk_bf16_f32 v207, v198, v199
	v_add_u32_e32 v156, 0x2c00, v156
	global_store_dwordx2 v156, v[206:207], s[18:19]
	v_lshlrev_b32_e32 v164, 16, v94
	v_and_b32_e32 v165, 0xffff0000, v94
	v_lshlrev_b32_e32 v166, 16, v95
	v_and_b32_e32 v167, 0xffff0000, v95
	v_lshlrev_b32_e32 v176, 16, v114
	v_and_b32_e32 v177, 0xffff0000, v114
	v_lshlrev_b32_e32 v178, 16, v115
	v_and_b32_e32 v179, 0xffff0000, v115
	v_pk_mul_f32 v[184:185], v[120:121], v[160:161]
	v_pk_mul_f32 v[188:189], v[136:137], v[172:173]
	v_pk_fma_f32 v[184:185], v[124:125], v[168:169], v[184:185]
	v_pk_fma_f32 v[188:189], v[140:141], v[180:181], v[188:189]
	v_pk_fma_f32 v[184:185], v[128:129], v[164:165], v[184:185]
	v_pk_fma_f32 v[188:189], v[144:145], v[176:177], v[188:189]
	v_pk_add_f32 v[184:185], v[184:185], v[132:133]
	v_pk_add_f32 v[188:189], v[188:189], v[148:149]
	v_pk_mul_f32 v[186:187], v[122:123], v[162:163]
	v_pk_mul_f32 v[190:191], v[138:139], v[174:175]
	v_pk_fma_f32 v[186:187], v[126:127], v[170:171], v[186:187]
	v_pk_fma_f32 v[190:191], v[142:143], v[182:183], v[190:191]
	v_pk_fma_f32 v[186:187], v[130:131], v[166:167], v[186:187]
	v_pk_fma_f32 v[190:191], v[146:147], v[178:179], v[190:191]
	v_pk_add_f32 v[186:187], v[186:187], v[134:135]
	v_pk_add_f32 v[190:191], v[190:191], v[150:151]
	v_mul_f32_e32 v192, 0xbfb8aa3b, v188
	v_mul_f32_e32 v193, 0xbfb8aa3b, v189
	v_mul_f32_e32 v194, 0xbfb8aa3b, v190
	v_mul_f32_e32 v195, 0xbfb8aa3b, v191
	v_exp_f32_e32 v192, v192
	v_exp_f32_e32 v193, v193
	v_exp_f32_e32 v194, v194
	v_exp_f32_e32 v195, v195
	s_nop 0
	v_pk_add_f32 v[192:193], v[192:193], 1.0 op_sel_hi:[1,0]
	v_pk_add_f32 v[194:195], v[194:195], 1.0 op_sel_hi:[1,0]
	v_div_scale_f32 v200, s[8:9], v192, v192, 1.0
	v_div_scale_f32 v201, vcc, 1.0, v192, 1.0
	v_rcp_f32_e32 v202, v200
	s_nop 0
	v_fma_f32 v204, -v200, v202, 1.0
	v_fmac_f32_e32 v202, v204, v202
	v_mul_f32_e32 v203, v201, v202
	v_fma_f32 v204, -v200, v203, v201
	v_fmac_f32_e32 v203, v204, v202
	v_fma_f32 v204, -v200, v203, v201
	v_div_fmas_f32 v204, v204, v202, v203
	v_div_fixup_f32 v196, v204, v192, 1.0
	v_div_scale_f32 v200, s[8:9], v193, v193, 1.0
	v_div_scale_f32 v201, vcc, 1.0, v193, 1.0
	v_rcp_f32_e32 v202, v200
	s_nop 0
	v_fma_f32 v204, -v200, v202, 1.0
	v_fmac_f32_e32 v202, v204, v202
	v_mul_f32_e32 v203, v201, v202
	v_fma_f32 v204, -v200, v203, v201
	v_fmac_f32_e32 v203, v204, v202
	v_fma_f32 v204, -v200, v203, v201
	v_div_fmas_f32 v204, v204, v202, v203
	v_div_fixup_f32 v197, v204, v193, 1.0
	v_div_scale_f32 v200, s[8:9], v194, v194, 1.0
	v_div_scale_f32 v201, vcc, 1.0, v194, 1.0
	v_rcp_f32_e32 v202, v200
	s_nop 0
	v_fma_f32 v204, -v200, v202, 1.0
	v_fmac_f32_e32 v202, v204, v202
	v_mul_f32_e32 v203, v201, v202
	v_fma_f32 v204, -v200, v203, v201
	v_fmac_f32_e32 v203, v204, v202
	v_fma_f32 v204, -v200, v203, v201
	v_div_fmas_f32 v204, v204, v202, v203
	v_div_fixup_f32 v198, v204, v194, 1.0
	v_div_scale_f32 v200, s[8:9], v195, v195, 1.0
	v_div_scale_f32 v201, vcc, 1.0, v195, 1.0
	v_rcp_f32_e32 v202, v200
	s_nop 0
	v_fma_f32 v204, -v200, v202, 1.0
	v_fmac_f32_e32 v202, v204, v202
	v_mul_f32_e32 v203, v201, v202
	v_fma_f32 v204, -v200, v203, v201
	v_fmac_f32_e32 v203, v204, v202
	v_fma_f32 v204, -v200, v203, v201
	v_div_fmas_f32 v204, v204, v202, v203
	v_div_fixup_f32 v199, v204, v195, 1.0
	v_pk_mul_f32 v[196:197], v[188:189], v[196:197]
	v_pk_mul_f32 v[198:199], v[190:191], v[198:199]
	v_pk_mul_f32 v[196:197], v[184:185], v[196:197]
	v_pk_mul_f32 v[198:199], v[186:187], v[198:199]
	v_cvt_pk_bf16_f32 v208, v196, v197
	v_cvt_pk_bf16_f32 v209, v198, v199
	v_add_u32_e32 v156, 0x2c00, v156
	global_store_dwordx2 v156, v[208:209], s[18:19]
	v_lshlrev_b32_e32 v168, 16, v96
	v_and_b32_e32 v169, 0xffff0000, v96
	v_lshlrev_b32_e32 v170, 16, v97
	v_and_b32_e32 v171, 0xffff0000, v97
	v_lshlrev_b32_e32 v180, 16, v116
	v_and_b32_e32 v181, 0xffff0000, v116
	v_lshlrev_b32_e32 v182, 16, v117
	v_and_b32_e32 v183, 0xffff0000, v117
	v_pk_mul_f32 v[184:185], v[120:121], v[164:165]
	v_pk_mul_f32 v[188:189], v[136:137], v[176:177]
	v_pk_fma_f32 v[184:185], v[124:125], v[160:161], v[184:185]
	v_pk_fma_f32 v[188:189], v[140:141], v[172:173], v[188:189]
	v_pk_fma_f32 v[184:185], v[128:129], v[168:169], v[184:185]
	v_pk_fma_f32 v[188:189], v[144:145], v[180:181], v[188:189]
	v_pk_add_f32 v[184:185], v[184:185], v[132:133]
	v_pk_add_f32 v[188:189], v[188:189], v[148:149]
	v_pk_mul_f32 v[186:187], v[122:123], v[166:167]
	v_pk_mul_f32 v[190:191], v[138:139], v[178:179]
	v_pk_fma_f32 v[186:187], v[126:127], v[162:163], v[186:187]
	v_pk_fma_f32 v[190:191], v[142:143], v[174:175], v[190:191]
	v_pk_fma_f32 v[186:187], v[130:131], v[170:171], v[186:187]
	v_pk_fma_f32 v[190:191], v[146:147], v[182:183], v[190:191]
	v_pk_add_f32 v[186:187], v[186:187], v[134:135]
	v_pk_add_f32 v[190:191], v[190:191], v[150:151]
	v_mul_f32_e32 v192, 0xbfb8aa3b, v188
	v_mul_f32_e32 v193, 0xbfb8aa3b, v189
	v_mul_f32_e32 v194, 0xbfb8aa3b, v190
	v_mul_f32_e32 v195, 0xbfb8aa3b, v191
	v_exp_f32_e32 v192, v192
	v_exp_f32_e32 v193, v193
	v_exp_f32_e32 v194, v194
	v_exp_f32_e32 v195, v195
	s_nop 0
	v_pk_add_f32 v[192:193], v[192:193], 1.0 op_sel_hi:[1,0]
	v_pk_add_f32 v[194:195], v[194:195], 1.0 op_sel_hi:[1,0]
	v_div_scale_f32 v200, s[8:9], v192, v192, 1.0
	v_div_scale_f32 v201, vcc, 1.0, v192, 1.0
	v_rcp_f32_e32 v202, v200
	s_nop 0
	v_fma_f32 v204, -v200, v202, 1.0
	v_fmac_f32_e32 v202, v204, v202
	v_mul_f32_e32 v203, v201, v202
	v_fma_f32 v204, -v200, v203, v201
	v_fmac_f32_e32 v203, v204, v202
	v_fma_f32 v204, -v200, v203, v201
	v_div_fmas_f32 v204, v204, v202, v203
	v_div_fixup_f32 v196, v204, v192, 1.0
	v_div_scale_f32 v200, s[8:9], v193, v193, 1.0
	v_div_scale_f32 v201, vcc, 1.0, v193, 1.0
	v_rcp_f32_e32 v202, v200
	s_nop 0
	v_fma_f32 v204, -v200, v202, 1.0
	v_fmac_f32_e32 v202, v204, v202
	v_mul_f32_e32 v203, v201, v202
	v_fma_f32 v204, -v200, v203, v201
	v_fmac_f32_e32 v203, v204, v202
	v_fma_f32 v204, -v200, v203, v201
	v_div_fmas_f32 v204, v204, v202, v203
	v_div_fixup_f32 v197, v204, v193, 1.0
	v_div_scale_f32 v200, s[8:9], v194, v194, 1.0
	v_div_scale_f32 v201, vcc, 1.0, v194, 1.0
	v_rcp_f32_e32 v202, v200
	s_nop 0
	v_fma_f32 v204, -v200, v202, 1.0
	v_fmac_f32_e32 v202, v204, v202
	v_mul_f32_e32 v203, v201, v202
	v_fma_f32 v204, -v200, v203, v201
	v_fmac_f32_e32 v203, v204, v202
	v_fma_f32 v204, -v200, v203, v201
	v_div_fmas_f32 v204, v204, v202, v203
	v_div_fixup_f32 v198, v204, v194, 1.0
	v_div_scale_f32 v200, s[8:9], v195, v195, 1.0
	v_div_scale_f32 v201, vcc, 1.0, v195, 1.0
	v_rcp_f32_e32 v202, v200
	s_nop 0
	v_fma_f32 v204, -v200, v202, 1.0
	v_fmac_f32_e32 v202, v204, v202
	v_mul_f32_e32 v203, v201, v202
	v_fma_f32 v204, -v200, v203, v201
	v_fmac_f32_e32 v203, v204, v202
	v_fma_f32 v204, -v200, v203, v201
	v_div_fmas_f32 v204, v204, v202, v203
	v_div_fixup_f32 v199, v204, v195, 1.0
	v_pk_mul_f32 v[196:197], v[188:189], v[196:197]
	v_pk_mul_f32 v[198:199], v[190:191], v[198:199]
	v_pk_mul_f32 v[196:197], v[184:185], v[196:197]
	v_pk_mul_f32 v[198:199], v[186:187], v[198:199]
	v_cvt_pk_bf16_f32 v206, v196, v197
	v_cvt_pk_bf16_f32 v207, v198, v199
	v_add_u32_e32 v156, 0x2c00, v156
	global_store_dwordx2 v156, v[206:207], s[18:19]
	v_lshlrev_b32_e32 v160, 16, v98
	v_and_b32_e32 v161, 0xffff0000, v98
	v_lshlrev_b32_e32 v162, 16, v99
	v_and_b32_e32 v163, 0xffff0000, v99
	v_lshlrev_b32_e32 v172, 16, v118
	v_and_b32_e32 v173, 0xffff0000, v118
	v_lshlrev_b32_e32 v174, 16, v119
	v_and_b32_e32 v175, 0xffff0000, v119
	v_pk_mul_f32 v[184:185], v[120:121], v[168:169]
	v_pk_mul_f32 v[188:189], v[136:137], v[180:181]
	v_pk_fma_f32 v[184:185], v[124:125], v[164:165], v[184:185]
	v_pk_fma_f32 v[188:189], v[140:141], v[176:177], v[188:189]
	v_pk_fma_f32 v[184:185], v[128:129], v[160:161], v[184:185]
	v_pk_fma_f32 v[188:189], v[144:145], v[172:173], v[188:189]
	v_pk_add_f32 v[184:185], v[184:185], v[132:133]
	v_pk_add_f32 v[188:189], v[188:189], v[148:149]
	v_pk_mul_f32 v[186:187], v[122:123], v[170:171]
	v_pk_mul_f32 v[190:191], v[138:139], v[182:183]
	v_pk_fma_f32 v[186:187], v[126:127], v[166:167], v[186:187]
	v_pk_fma_f32 v[190:191], v[142:143], v[178:179], v[190:191]
	v_pk_fma_f32 v[186:187], v[130:131], v[162:163], v[186:187]
	v_pk_fma_f32 v[190:191], v[146:147], v[174:175], v[190:191]
	v_pk_add_f32 v[186:187], v[186:187], v[134:135]
	v_pk_add_f32 v[190:191], v[190:191], v[150:151]
	v_mul_f32_e32 v192, 0xbfb8aa3b, v188
	v_mul_f32_e32 v193, 0xbfb8aa3b, v189
	v_mul_f32_e32 v194, 0xbfb8aa3b, v190
	v_mul_f32_e32 v195, 0xbfb8aa3b, v191
	v_exp_f32_e32 v192, v192
	v_exp_f32_e32 v193, v193
	v_exp_f32_e32 v194, v194
	v_exp_f32_e32 v195, v195
	s_nop 0
	v_pk_add_f32 v[192:193], v[192:193], 1.0 op_sel_hi:[1,0]
	v_pk_add_f32 v[194:195], v[194:195], 1.0 op_sel_hi:[1,0]
	v_div_scale_f32 v200, s[8:9], v192, v192, 1.0
	v_div_scale_f32 v201, vcc, 1.0, v192, 1.0
	v_rcp_f32_e32 v202, v200
	s_nop 0
	v_fma_f32 v204, -v200, v202, 1.0
	v_fmac_f32_e32 v202, v204, v202
	v_mul_f32_e32 v203, v201, v202
	v_fma_f32 v204, -v200, v203, v201
	v_fmac_f32_e32 v203, v204, v202
	v_fma_f32 v204, -v200, v203, v201
	v_div_fmas_f32 v204, v204, v202, v203
	v_div_fixup_f32 v196, v204, v192, 1.0
	v_div_scale_f32 v200, s[8:9], v193, v193, 1.0
	v_div_scale_f32 v201, vcc, 1.0, v193, 1.0
	v_rcp_f32_e32 v202, v200
	s_nop 0
	v_fma_f32 v204, -v200, v202, 1.0
	v_fmac_f32_e32 v202, v204, v202
	v_mul_f32_e32 v203, v201, v202
	v_fma_f32 v204, -v200, v203, v201
	v_fmac_f32_e32 v203, v204, v202
	v_fma_f32 v204, -v200, v203, v201
	v_div_fmas_f32 v204, v204, v202, v203
	v_div_fixup_f32 v197, v204, v193, 1.0
	v_div_scale_f32 v200, s[8:9], v194, v194, 1.0
	v_div_scale_f32 v201, vcc, 1.0, v194, 1.0
	v_rcp_f32_e32 v202, v200
	s_nop 0
	v_fma_f32 v204, -v200, v202, 1.0
	v_fmac_f32_e32 v202, v204, v202
	v_mul_f32_e32 v203, v201, v202
	v_fma_f32 v204, -v200, v203, v201
	v_fmac_f32_e32 v203, v204, v202
	v_fma_f32 v204, -v200, v203, v201
	v_div_fmas_f32 v204, v204, v202, v203
	v_div_fixup_f32 v198, v204, v194, 1.0
	v_div_scale_f32 v200, s[8:9], v195, v195, 1.0
	v_div_scale_f32 v201, vcc, 1.0, v195, 1.0
	v_rcp_f32_e32 v202, v200
	s_nop 0
	v_fma_f32 v204, -v200, v202, 1.0
	v_fmac_f32_e32 v202, v204, v202
	v_mul_f32_e32 v203, v201, v202
	v_fma_f32 v204, -v200, v203, v201
	v_fmac_f32_e32 v203, v204, v202
	v_fma_f32 v204, -v200, v203, v201
	v_div_fmas_f32 v204, v204, v202, v203
	v_div_fixup_f32 v199, v204, v195, 1.0
	v_pk_mul_f32 v[196:197], v[188:189], v[196:197]
	v_pk_mul_f32 v[198:199], v[190:191], v[198:199]
	v_pk_mul_f32 v[196:197], v[184:185], v[196:197]
	v_pk_mul_f32 v[198:199], v[186:187], v[198:199]
	v_cvt_pk_bf16_f32 v208, v196, v197
	v_cvt_pk_bf16_f32 v209, v198, v199
	v_add_u32_e32 v156, 0x2c00, v156
	global_store_dwordx2 v156, v[208:209], s[18:19]
	s_mov_b64 exec, s[38:39]
	s_mov_b32 s38, 0x2e8ba2e9
	s_mov_b32 s39, 0x160000
	s_cbranch_execz .Lcv_done
	s_branch .Lcv_loop
.Lcv_done:
.LBB0_1011:
	s_or_b64 exec, exec, s[12:13]
